# GEMM K-loops: priority inverted - s_setprio 1 during the load segments (ds_read + LDS-DMA issue), priority 0 during MFMA segments; on top of 4/4 staging rebalance + saddr DMA
# baseline (speedup 1.0000x reference)
; #define PG8_STAGE(bufoff, gbase, voff) do { _Pragma("unroll") for (int _i = 0; _i < 2; ++_i) \
;         __builtin_amdgcn_global_load_lds((const unsigned*)((const char*)(gbase) + (voff)[_i]), (LAS unsigned*)(lds + (bufoff) + ldsw + _i * 8192), 16, 0, 0); } while (0)
; #define PG8_LDA(dst, b, h) do { _Pragma("unroll") for (int m = 0; m < 4; ++m) _Pragma("unroll") for (int k = 0; k < 2; ++k) dst[m][k] = *(const LAS bf16x8*)(lds + PG8_SA(b, h) + aoff + m * 2048 + k * 1024); } while (0)
; #define PG8_LDB(dst, b, h) do { _Pragma("unroll") for (int n = 0; n < 2; ++n) _Pragma("unroll") for (int k = 0; k < 2; ++k) dst[n][k] = *(const LAS bf16x8*)(lds + PG8_SB(b, h) + boff + n * 2048 + k * 1024); } while (0)
; #define PG8_WAIT_V(n) asm volatile("s_waitcnt vmcnt(" #n ")" ::: "memory")
; #define PG8_WAIT_L(n) asm volatile("s_waitcnt lgkmcnt(" #n ")" ::: "memory")
; #define PG8_BAR __builtin_amdgcn_s_barrier()
; #define PG8_SCHED __builtin_amdgcn_sched_barrier(0)
; template <class Epi, class Sched, bool I8 = false>
; __device__ __forceinline__ void gemm_phase(LAS unsigned char* lds, const Gemm g, const Sched& S, const Epi& E) {
;     ...
;             PG8_LDB(B0, 0, 0); PG8_LDB(B1, 0, 1); PG8_SCHED; PG8_LDA(At, 0, 0); PG8_STAGE(PG8_SA(1, 1), a1 + hstepA, voffA);
;             PG8_WAIT_V(8); PG8_WAIT_L(0); PG8_BAR; PG8_MMA(0, 0, At, B0); PG8_MMA(0, 1, At, B1); PG8_BAR; PG8_SCHED;
;             PG8_LDA(At, 0, 1); PG8_STAGE(PG8_SB(0, 0), b2, voffB); PG8_STAGE(PG8_SB(0, 1), b2 + hstepB, voffB); PG8_STAGE(PG8_SA(0, 0), a2, voffA);
;             PG8_WAIT_V(8); PG8_WAIT_L(0); PG8_BAR; PG8_MMA(1, 0, At, B0); PG8_MMA(1, 1, At, B1); PG8_BAR; PG8_SCHED;
.LBB0_1169:
	s_setprio 1
	ds_read_b128 v[90:93], v169
	ds_read_b128 v[98:101], v169 offset:1024
	ds_read_b128 v[172:175], v169 offset:2048
	ds_read_b128 v[176:179], v169 offset:3072
	ds_read_b128 v[180:183], v170
	ds_read_b128 v[184:187], v170 offset:1024
	ds_read_b128 v[188:191], v170 offset:2048
	ds_read_b128 v[192:195], v170 offset:3072
	s_add_u32 s22, s20, 0x4000
	s_addc_u32 s23, s21, 0
	s_cmp_eq_u32 s53, 28
	s_cselect_b32 s26, s49, s22
	s_cselect_b32 s27, s13, s23
	s_cselect_b32 s24, s50, s51
	s_cselect_b32 s25, s11, s52
	s_add_u32 s22, s26, 0x8000
	s_addc_u32 s23, s27, 0
	s_sub_u32 s98, s20, 0x4000
	s_subb_u32 s99, s21, 0
	s_mov_b32 m0, s43
	s_nop 0
	global_load_lds_dwordx4 v144, s[98:99]
	s_mov_b32 m0, s44
	s_nop 0
	global_load_lds_dwordx4 v140, s[98:99]
	s_add_i32 m0, s36, 0xc000
	ds_read_b128 v[196:199], v171
	ds_read_b128 v[200:203], v171 offset:1024
	ds_read_b128 v[204:207], v171 offset:2048
	ds_read_b128 v[208:211], v171 offset:3072
	ds_read_b128 v[212:215], v171 offset:4096
	ds_read_b128 v[216:219], v171 offset:5120
	ds_read_b128 v[220:223], v171 offset:6144
	ds_read_b128 v[224:227], v171 offset:7168
	global_load_lds_dwordx4 v148, s[20:21]
	s_add_i32 m0, s36, 0xe000
	s_nop 0
	global_load_lds_dwordx4 v150, s[20:21]
	s_setprio 0
	s_waitcnt vmcnt(8)
	s_waitcnt lgkmcnt(0)
	s_barrier
	s_waitcnt lgkmcnt(0)
	v_mfma_i32_16x16x64_i8 v[134:137], v[90:93], v[196:199], v[134:137]
	v_mfma_i32_16x16x64_i8 v[130:133], v[172:175], v[196:199], v[130:133]
	v_mfma_i32_16x16x64_i8 v[118:121], v[90:93], v[204:207], v[118:121]
	v_mfma_i32_16x16x64_i8 v[114:117], v[172:175], v[204:207], v[114:117]
	v_mfma_i32_16x16x64_i8 v[102:105], v[90:93], v[212:215], v[102:105]
	v_mfma_i32_16x16x64_i8 v[94:97], v[172:175], v[212:215], v[94:97]
	v_mfma_i32_16x16x64_i8 v[78:81], v[90:93], v[220:223], v[78:81]
	v_mfma_i32_16x16x64_i8 v[74:77], v[172:175], v[220:223], v[74:77]
	v_mfma_i32_16x16x64_i8 v[134:137], v[98:101], v[200:203], v[134:137]
	v_mfma_i32_16x16x64_i8 v[130:133], v[176:179], v[200:203], v[130:133]
	v_mfma_i32_16x16x64_i8 v[118:121], v[98:101], v[208:211], v[118:121]
	v_mfma_i32_16x16x64_i8 v[114:117], v[176:179], v[208:211], v[114:117]
	v_mfma_i32_16x16x64_i8 v[102:105], v[98:101], v[216:219], v[102:105]
	v_mfma_i32_16x16x64_i8 v[94:97], v[176:179], v[216:219], v[94:97]
	v_mfma_i32_16x16x64_i8 v[78:81], v[98:101], v[224:227], v[78:81]
	v_mfma_i32_16x16x64_i8 v[74:77], v[176:179], v[224:227], v[74:77]
	v_mfma_i32_16x16x64_i8 v[126:129], v[180:183], v[196:199], v[126:129]
	v_mfma_i32_16x16x64_i8 v[122:125], v[188:191], v[196:199], v[122:125]
	v_mfma_i32_16x16x64_i8 v[110:113], v[180:183], v[204:207], v[110:113]
	v_mfma_i32_16x16x64_i8 v[106:109], v[188:191], v[204:207], v[106:109]
	v_mfma_i32_16x16x64_i8 v[86:89], v[180:183], v[212:215], v[86:89]
	v_mfma_i32_16x16x64_i8 v[82:85], v[188:191], v[212:215], v[82:85]
	v_mfma_i32_16x16x64_i8 v[70:73], v[180:183], v[220:223], v[70:73]
	v_mfma_i32_16x16x64_i8 v[66:69], v[188:191], v[220:223], v[66:69]
	v_mfma_i32_16x16x64_i8 v[126:129], v[184:187], v[200:203], v[126:129]
	v_mfma_i32_16x16x64_i8 v[122:125], v[192:195], v[200:203], v[122:125]
	v_mfma_i32_16x16x64_i8 v[110:113], v[184:187], v[208:211], v[110:113]
	v_mfma_i32_16x16x64_i8 v[106:109], v[192:195], v[208:211], v[106:109]
	v_mfma_i32_16x16x64_i8 v[86:89], v[184:187], v[216:219], v[86:89]
	v_mfma_i32_16x16x64_i8 v[82:85], v[192:195], v[216:219], v[82:85]
	v_mfma_i32_16x16x64_i8 v[70:73], v[184:187], v[224:227], v[70:73]
	v_mfma_i32_16x16x64_i8 v[66:69], v[192:195], v[224:227], v[66:69]
	s_barrier
	s_setprio 1
	s_add_i32 s54, s46, s33
	s_mov_b32 m0, s54
	ds_read_b128 v[196:199], v171 offset:16384
	ds_read_b128 v[200:203], v171 offset:17408
	ds_read_b128 v[204:207], v171 offset:18432
	ds_read_b128 v[208:211], v171 offset:19456
	ds_read_b128 v[212:215], v171 offset:20480
	ds_read_b128 v[216:219], v171 offset:21504
	ds_read_b128 v[220:223], v171 offset:22528
	ds_read_b128 v[224:227], v171 offset:23552
	global_load_lds_dwordx4 v142, s[24:25]
	s_add_i32 m0, s54, 0x2000
	s_add_u32 s54, s24, 0x4000
	s_addc_u32 s55, s25, 0
	s_add_i32 s56, s47, s33
	global_load_lds_dwordx4 v138, s[24:25]
	s_mov_b32 m0, s56
	s_nop 0
	global_load_lds_dwordx4 v142, s[54:55]
	s_add_i32 m0, s56, 0x2000
	s_nop 0
	global_load_lds_dwordx4 v138, s[54:55]
	s_setprio 0
	s_waitcnt vmcnt(6)
	s_waitcnt lgkmcnt(0)
	s_barrier
	s_waitcnt lgkmcnt(0)
	v_mfma_i32_16x16x64_i8 v[62:65], v[90:93], v[196:199], v[62:65]
	v_mfma_i32_16x16x64_i8 v[58:61], v[172:175], v[196:199], v[58:61]
	v_mfma_i32_16x16x64_i8 v[46:49], v[90:93], v[204:207], v[46:49]
	v_mfma_i32_16x16x64_i8 v[42:45], v[172:175], v[204:207], v[42:45]
	v_mfma_i32_16x16x64_i8 v[30:33], v[90:93], v[212:215], v[30:33]
	v_mfma_i32_16x16x64_i8 v[26:29], v[172:175], v[212:215], v[26:29]
	v_mfma_i32_16x16x64_i8 v[14:17], v[90:93], v[220:223], v[14:17]
	v_mfma_i32_16x16x64_i8 v[10:13], v[172:175], v[220:223], v[10:13]
	v_mfma_i32_16x16x64_i8 v[62:65], v[98:101], v[200:203], v[62:65]
	v_mfma_i32_16x16x64_i8 v[58:61], v[176:179], v[200:203], v[58:61]
	v_mfma_i32_16x16x64_i8 v[46:49], v[98:101], v[208:211], v[46:49]
	v_mfma_i32_16x16x64_i8 v[42:45], v[176:179], v[208:211], v[42:45]
	v_mfma_i32_16x16x64_i8 v[30:33], v[98:101], v[216:219], v[30:33]
	v_mfma_i32_16x16x64_i8 v[26:29], v[176:179], v[216:219], v[26:29]
	v_mfma_i32_16x16x64_i8 v[14:17], v[98:101], v[224:227], v[14:17]
	v_mfma_i32_16x16x64_i8 v[10:13], v[176:179], v[224:227], v[10:13]
	v_mfma_i32_16x16x64_i8 v[54:57], v[180:183], v[196:199], v[54:57]
	v_mfma_i32_16x16x64_i8 v[50:53], v[188:191], v[196:199], v[50:53]
	v_mfma_i32_16x16x64_i8 v[38:41], v[180:183], v[204:207], v[38:41]
	v_mfma_i32_16x16x64_i8 v[34:37], v[188:191], v[204:207], v[34:37]
	v_mfma_i32_16x16x64_i8 v[22:25], v[180:183], v[212:215], v[22:25]
	v_mfma_i32_16x16x64_i8 v[18:21], v[188:191], v[212:215], v[18:21]
	v_mfma_i32_16x16x64_i8 v[6:9], v[180:183], v[220:223], v[6:9]
	v_mfma_i32_16x16x64_i8 v[2:5], v[188:191], v[220:223], v[2:5]
	v_mfma_i32_16x16x64_i8 v[54:57], v[184:187], v[200:203], v[54:57]
	v_mfma_i32_16x16x64_i8 v[50:53], v[192:195], v[200:203], v[50:53]
	v_mfma_i32_16x16x64_i8 v[38:41], v[184:187], v[208:211], v[38:41]
	v_mfma_i32_16x16x64_i8 v[34:37], v[192:195], v[208:211], v[34:37]
	v_mfma_i32_16x16x64_i8 v[22:25], v[184:187], v[216:219], v[22:25]
	v_mfma_i32_16x16x64_i8 v[18:21], v[192:195], v[216:219], v[18:21]
	v_mfma_i32_16x16x64_i8 v[6:9], v[184:187], v[224:227], v[6:9]
	v_mfma_i32_16x16x64_i8 v[2:5], v[192:195], v[224:227], v[2:5]
	s_barrier
; #define PG8_STAGE(bufoff, gbase, voff) do { _Pragma("unroll") for (int _i = 0; _i < 2; ++_i) \
;         __builtin_amdgcn_global_load_lds((const unsigned*)((const char*)(gbase) + (voff)[_i]), (LAS unsigned*)(lds + (bufoff) + ldsw + _i * 8192), 16, 0, 0); } while (0)
; #define PG8_LDA(dst, b, h) do { _Pragma("unroll") for (int m = 0; m < 4; ++m) _Pragma("unroll") for (int k = 0; k < 2; ++k) dst[m][k] = *(const LAS bf16x8*)(lds + PG8_SA(b, h) + aoff + m * 2048 + k * 1024); } while (0)
; #define PG8_LDB(dst, b, h) do { _Pragma("unroll") for (int n = 0; n < 2; ++n) _Pragma("unroll") for (int k = 0; k < 2; ++k) dst[n][k] = *(const LAS bf16x8*)(lds + PG8_SB(b, h) + boff + n * 2048 + k * 1024); } while (0)
; #define PG8_WAIT_V(n) asm volatile("s_waitcnt vmcnt(" #n ")" ::: "memory")
; #define PG8_WAIT_L(n) asm volatile("s_waitcnt lgkmcnt(" #n ")" ::: "memory")
; #define PG8_BAR __builtin_amdgcn_s_barrier()
; #define PG8_SCHED __builtin_amdgcn_sched_barrier(0)
; template <class Epi, class Sched, bool I8 = false>
; __device__ __forceinline__ void gemm_phase(LAS unsigned char* lds, const Gemm g, const Sched& S, const Epi& E) {
;     ...
;         for (int t = 0; t < nt; t += 2) {
;             const bool last = (t == nt - 2);
;     ...
;             PG8_LDB(B0, 1, 0); PG8_LDB(B1, 1, 1); PG8_SCHED; PG8_LDA(At, 1, 0); PG8_STAGE(PG8_SA(0, 1), a2 + hstepA, voffA);
;             PG8_WAIT_V(8); PG8_WAIT_L(0); PG8_BAR; PG8_MMA(0, 0, At, B0); PG8_MMA(0, 1, At, B1); PG8_BAR; PG8_SCHED;
;             PG8_LDA(At, 1, 1); PG8_STAGE(PG8_SB(1, 0), b3, voffB); PG8_STAGE(PG8_SB(1, 1), b3 + hstepB, voffB); PG8_STAGE(PG8_SA(1, 0), a3, voffA);
;             PG8_WAIT_V(8); PG8_WAIT_L(0); PG8_BAR; PG8_MMA(1, 0, At, B0); PG8_MMA(1, 1, At, B1); PG8_BAR; PG8_SCHED;
	s_setprio 1
	s_add_i32 s54, 0, 0x18000
	v_add_u32_e32 v146, s54, v165
	s_add_i32 s55, 0, 0x1c000
	ds_read_b128 v[90:93], v146
	ds_read_b128 v[98:101], v146 offset:1024
	ds_read_b128 v[172:175], v146 offset:2048
	ds_read_b128 v[176:179], v146 offset:3072
	v_add_u32_e32 v146, s55, v165
	ds_read_b128 v[180:183], v146
	ds_read_b128 v[184:187], v146 offset:1024
	ds_read_b128 v[188:191], v146 offset:2048
	ds_read_b128 v[192:195], v146 offset:3072
	s_mov_b32 m0, s36
	s_nop 0
	global_load_lds_dwordx4 v144, s[26:27]
	s_mov_b32 m0, s37
	s_nop 0
	global_load_lds_dwordx4 v140, s[26:27]
	s_add_u32 s26, s26, 0x4000
	s_addc_u32 s27, s27, 0
	s_mov_b32 m0, s38
	ds_read_b128 v[196:199], v171 offset:32768
	ds_read_b128 v[200:203], v171 offset:33792
	ds_read_b128 v[204:207], v171 offset:34816
	ds_read_b128 v[208:211], v171 offset:35840
	ds_read_b128 v[212:215], v171 offset:36864
	ds_read_b128 v[216:219], v171 offset:37888
	ds_read_b128 v[220:223], v171 offset:38912
	ds_read_b128 v[224:227], v171 offset:39936
	global_load_lds_dwordx4 v144, s[26:27]
	s_mov_b32 m0, s39
	s_nop 0
	global_load_lds_dwordx4 v140, s[26:27]
	s_setprio 0
	s_waitcnt vmcnt(8)
	s_waitcnt lgkmcnt(0)
	s_barrier
	s_waitcnt lgkmcnt(0)
	v_mfma_i32_16x16x64_i8 v[134:137], v[90:93], v[196:199], v[134:137]
	v_mfma_i32_16x16x64_i8 v[130:133], v[172:175], v[196:199], v[130:133]
	v_mfma_i32_16x16x64_i8 v[118:121], v[90:93], v[204:207], v[118:121]
	v_mfma_i32_16x16x64_i8 v[114:117], v[172:175], v[204:207], v[114:117]
	v_mfma_i32_16x16x64_i8 v[102:105], v[90:93], v[212:215], v[102:105]
	v_mfma_i32_16x16x64_i8 v[94:97], v[172:175], v[212:215], v[94:97]
	v_mfma_i32_16x16x64_i8 v[78:81], v[90:93], v[220:223], v[78:81]
	v_mfma_i32_16x16x64_i8 v[74:77], v[172:175], v[220:223], v[74:77]
	v_mfma_i32_16x16x64_i8 v[134:137], v[98:101], v[200:203], v[134:137]
	v_mfma_i32_16x16x64_i8 v[130:133], v[176:179], v[200:203], v[130:133]
	v_mfma_i32_16x16x64_i8 v[118:121], v[98:101], v[208:211], v[118:121]
	v_mfma_i32_16x16x64_i8 v[114:117], v[176:179], v[208:211], v[114:117]
	v_mfma_i32_16x16x64_i8 v[102:105], v[98:101], v[216:219], v[102:105]
	v_mfma_i32_16x16x64_i8 v[94:97], v[176:179], v[216:219], v[94:97]
	v_mfma_i32_16x16x64_i8 v[78:81], v[98:101], v[224:227], v[78:81]
	v_mfma_i32_16x16x64_i8 v[74:77], v[176:179], v[224:227], v[74:77]
	v_mfma_i32_16x16x64_i8 v[126:129], v[180:183], v[196:199], v[126:129]
	v_mfma_i32_16x16x64_i8 v[122:125], v[188:191], v[196:199], v[122:125]
	v_mfma_i32_16x16x64_i8 v[110:113], v[180:183], v[204:207], v[110:113]
	v_mfma_i32_16x16x64_i8 v[106:109], v[188:191], v[204:207], v[106:109]
	v_mfma_i32_16x16x64_i8 v[86:89], v[180:183], v[212:215], v[86:89]
	v_mfma_i32_16x16x64_i8 v[82:85], v[188:191], v[212:215], v[82:85]
	v_mfma_i32_16x16x64_i8 v[70:73], v[180:183], v[220:223], v[70:73]
	v_mfma_i32_16x16x64_i8 v[66:69], v[188:191], v[220:223], v[66:69]
	v_mfma_i32_16x16x64_i8 v[126:129], v[184:187], v[200:203], v[126:129]
	v_mfma_i32_16x16x64_i8 v[122:125], v[192:195], v[200:203], v[122:125]
	v_mfma_i32_16x16x64_i8 v[110:113], v[184:187], v[208:211], v[110:113]
	v_mfma_i32_16x16x64_i8 v[106:109], v[192:195], v[208:211], v[106:109]
	v_mfma_i32_16x16x64_i8 v[86:89], v[184:187], v[216:219], v[86:89]
	v_mfma_i32_16x16x64_i8 v[82:85], v[192:195], v[216:219], v[82:85]
	v_mfma_i32_16x16x64_i8 v[70:73], v[184:187], v[224:227], v[70:73]
	v_mfma_i32_16x16x64_i8 v[66:69], v[192:195], v[224:227], v[66:69]
	s_barrier
	s_setprio 1
	s_add_u32 s26, s24, 0x8000
	s_addc_u32 s27, s25, 0
	s_add_i32 s54, s54, s33
	s_mov_b32 m0, s54
	ds_read_b128 v[196:199], v171 offset:49152
	ds_read_b128 v[200:203], v171 offset:50176
	ds_read_b128 v[204:207], v171 offset:51200
	ds_read_b128 v[208:211], v171 offset:52224
	ds_read_b128 v[212:215], v171 offset:53248
	ds_read_b128 v[216:219], v171 offset:54272
	ds_read_b128 v[220:223], v171 offset:55296
	ds_read_b128 v[224:227], v171 offset:56320
	global_load_lds_dwordx4 v142, s[26:27]
	s_add_i32 m0, s54, 0x2000
	s_add_u32 s24, s24, 0xc000
	v_lshl_add_u64 v[158:159], s[26:27], 0, v[138:139]
	s_addc_u32 s25, s25, 0
	s_add_i32 s26, s55, s33
	global_load_lds_dwordx4 v[158:159], off
	s_mov_b32 m0, s26
	s_nop 0
	global_load_lds_dwordx4 v142, s[24:25]
	s_add_i32 m0, s26, 0x2000
	s_nop 0
	global_load_lds_dwordx4 v138, s[24:25]
	s_setprio 0
	s_waitcnt vmcnt(6)
	s_waitcnt lgkmcnt(0)
	s_barrier
	s_waitcnt lgkmcnt(0)
	v_mfma_i32_16x16x64_i8 v[62:65], v[90:93], v[196:199], v[62:65]
	v_mfma_i32_16x16x64_i8 v[58:61], v[172:175], v[196:199], v[58:61]
	v_mfma_i32_16x16x64_i8 v[46:49], v[90:93], v[204:207], v[46:49]
	v_mfma_i32_16x16x64_i8 v[42:45], v[172:175], v[204:207], v[42:45]
	v_mfma_i32_16x16x64_i8 v[30:33], v[90:93], v[212:215], v[30:33]
	v_mfma_i32_16x16x64_i8 v[26:29], v[172:175], v[212:215], v[26:29]
	v_mfma_i32_16x16x64_i8 v[14:17], v[90:93], v[220:223], v[14:17]
	v_mfma_i32_16x16x64_i8 v[10:13], v[172:175], v[220:223], v[10:13]
	v_mfma_i32_16x16x64_i8 v[62:65], v[98:101], v[200:203], v[62:65]
	v_mfma_i32_16x16x64_i8 v[58:61], v[176:179], v[200:203], v[58:61]
	v_mfma_i32_16x16x64_i8 v[46:49], v[98:101], v[208:211], v[46:49]
	v_mfma_i32_16x16x64_i8 v[42:45], v[176:179], v[208:211], v[42:45]
	v_mfma_i32_16x16x64_i8 v[30:33], v[98:101], v[216:219], v[30:33]
	v_mfma_i32_16x16x64_i8 v[26:29], v[176:179], v[216:219], v[26:29]
	v_mfma_i32_16x16x64_i8 v[14:17], v[98:101], v[224:227], v[14:17]
	v_mfma_i32_16x16x64_i8 v[10:13], v[176:179], v[224:227], v[10:13]
	v_mfma_i32_16x16x64_i8 v[54:57], v[180:183], v[196:199], v[54:57]
	v_mfma_i32_16x16x64_i8 v[50:53], v[188:191], v[196:199], v[50:53]
	v_mfma_i32_16x16x64_i8 v[38:41], v[180:183], v[204:207], v[38:41]
	v_mfma_i32_16x16x64_i8 v[34:37], v[188:191], v[204:207], v[34:37]
	v_mfma_i32_16x16x64_i8 v[22:25], v[180:183], v[212:215], v[22:25]
	v_mfma_i32_16x16x64_i8 v[18:21], v[188:191], v[212:215], v[18:21]
	v_mfma_i32_16x16x64_i8 v[6:9], v[180:183], v[220:223], v[6:9]
	v_mfma_i32_16x16x64_i8 v[2:5], v[188:191], v[220:223], v[2:5]
	v_mfma_i32_16x16x64_i8 v[54:57], v[184:187], v[200:203], v[54:57]
	v_mfma_i32_16x16x64_i8 v[50:53], v[192:195], v[200:203], v[50:53]
	v_mfma_i32_16x16x64_i8 v[38:41], v[184:187], v[208:211], v[38:41]
	v_mfma_i32_16x16x64_i8 v[34:37], v[192:195], v[208:211], v[34:37]
	v_mfma_i32_16x16x64_i8 v[22:25], v[184:187], v[216:219], v[22:25]
	v_mfma_i32_16x16x64_i8 v[18:21], v[192:195], v[216:219], v[18:21]
	v_mfma_i32_16x16x64_i8 v[6:9], v[184:187], v[224:227], v[6:9]
	v_mfma_i32_16x16x64_i8 v[2:5], v[192:195], v[224:227], v[2:5]
	s_barrier
	s_add_i32 s53, s53, 2
	s_add_u32 s20, s20, 0x10000
	s_addc_u32 s21, s21, 0
	s_add_u32 s51, s51, 0x10000
	s_addc_u32 s52, s52, 0
	s_cmp_gt_u32 s53, 29
	s_cbranch_scc0 .LBB0_1169
	s_and_b64 vcc, exec, s[8:9]
	s_cbranch_vccz .LBB0_1172
	s_barrier

; #define PG8_STAGE(bufoff, gbase, voff) do { _Pragma("unroll") for (int _i = 0; _i < 2; ++_i) \
;         __builtin_amdgcn_global_load_lds((const unsigned*)((const char*)(gbase) + (voff)[_i]), (LAS unsigned*)(lds + (bufoff) + ldsw + _i * 8192), 16, 0, 0); } while (0)
; #define PG8_LDA(dst, b, h) do { _Pragma("unroll") for (int m = 0; m < 4; ++m) _Pragma("unroll") for (int k = 0; k < 2; ++k) dst[m][k] = *(const LAS bf16x8*)(lds + PG8_SA(b, h) + aoff + m * 2048 + k * 1024); } while (0)
; #define PG8_LDB(dst, b, h) do { _Pragma("unroll") for (int n = 0; n < 2; ++n) _Pragma("unroll") for (int k = 0; k < 2; ++k) dst[n][k] = *(const LAS bf16x8*)(lds + PG8_SB(b, h) + boff + n * 2048 + k * 1024); } while (0)
; #define PG8_WAIT_V(n) asm volatile("s_waitcnt vmcnt(" #n ")" ::: "memory")
; #define PG8_WAIT_L(n) asm volatile("s_waitcnt lgkmcnt(" #n ")" ::: "memory")
; #define PG8_BAR __builtin_amdgcn_s_barrier()
; #define PG8_SCHED __builtin_amdgcn_sched_barrier(0)
; template <class Epi, class Sched, bool I8 = false>
; __device__ __forceinline__ void gemm_phase(LAS unsigned char* lds, const Gemm g, const Sched& S, const Epi& E) {
;     ...
;             PG8_LDB(B0, 0, 0); PG8_LDB(B1, 0, 1); PG8_SCHED; PG8_LDA(At, 0, 0); PG8_STAGE(PG8_SA(1, 1), a1 + hstepA, voffA);
;             PG8_WAIT_V(8); PG8_WAIT_L(0); PG8_BAR; PG8_MMA(0, 0, At, B0); PG8_MMA(0, 1, At, B1); PG8_BAR; PG8_SCHED;
;             PG8_LDA(At, 0, 1); PG8_STAGE(PG8_SB(0, 0), b2, voffB); PG8_STAGE(PG8_SB(0, 1), b2 + hstepB, voffB); PG8_STAGE(PG8_SA(0, 0), a2, voffA);
;             PG8_WAIT_V(8); PG8_WAIT_L(0); PG8_BAR; PG8_MMA(1, 0, At, B0); PG8_MMA(1, 1, At, B1); PG8_BAR; PG8_SCHED;
.LBB0_1393:
	s_setprio 1
	ds_read_b128 v[66:69], v180
	ds_read_b128 v[70:73], v180 offset:1024
	ds_read_b128 v[74:77], v180 offset:2048
	ds_read_b128 v[78:81], v180 offset:3072
	ds_read_b128 v[146:149], v181
	ds_read_b128 v[150:153], v181 offset:1024
	ds_read_b128 v[174:177], v181 offset:2048
	ds_read_b128 v[184:187], v181 offset:3072
	s_add_u32 s20, s18, 0x4000
	s_addc_u32 s21, s19, 0
	s_cmpk_eq_i32 s49, 0x52
	s_cselect_b32 s24, s0, s20
	s_cselect_b32 s25, s1, s21
	s_cselect_b32 s22, s16, s47
	s_cselect_b32 s23, s17, s48
	s_add_u32 s20, s24, 0x8000
	s_addc_u32 s21, s25, 0
	s_sub_u32 s98, s18, 0x4000
	s_subb_u32 s99, s19, 0
	s_mov_b32 m0, s37
	s_nop 0
	global_load_lds_dwordx4 v156, s[98:99]
	s_mov_b32 m0, s38
	s_nop 0
	global_load_lds_dwordx4 v160, s[98:99]
	s_add_i32 m0, s31, 0xc000
	ds_read_b128 v[188:191], v182
	ds_read_b128 v[192:195], v182 offset:1024
	ds_read_b128 v[196:199], v182 offset:2048
	ds_read_b128 v[200:203], v182 offset:3072
	ds_read_b128 v[204:207], v182 offset:4096
	ds_read_b128 v[208:211], v182 offset:5120
	ds_read_b128 v[212:215], v182 offset:6144
	ds_read_b128 v[216:219], v182 offset:7168
	global_load_lds_dwordx4 v166, s[18:19]
	s_add_i32 m0, s31, 0xe000
	s_nop 0
	global_load_lds_dwordx4 v168, s[18:19]
	s_setprio 0
	s_waitcnt vmcnt(8)
	s_waitcnt lgkmcnt(0)
	s_barrier
	s_waitcnt lgkmcnt(0)
	v_mfma_i32_16x16x64_i8 v[142:145], v[66:69], v[188:191], v[142:145]
	v_mfma_i32_16x16x64_i8 v[138:141], v[74:77], v[188:191], v[138:141]
	v_mfma_i32_16x16x64_i8 v[126:129], v[66:69], v[196:199], v[126:129]
	v_mfma_i32_16x16x64_i8 v[122:125], v[74:77], v[196:199], v[122:125]
	v_mfma_i32_16x16x64_i8 v[110:113], v[66:69], v[204:207], v[110:113]
	v_mfma_i32_16x16x64_i8 v[106:109], v[74:77], v[204:207], v[106:109]
	v_mfma_i32_16x16x64_i8 v[94:97], v[66:69], v[212:215], v[94:97]
	v_mfma_i32_16x16x64_i8 v[90:93], v[74:77], v[212:215], v[90:93]
	v_mfma_i32_16x16x64_i8 v[142:145], v[70:73], v[192:195], v[142:145]
	v_mfma_i32_16x16x64_i8 v[138:141], v[78:81], v[192:195], v[138:141]
	v_mfma_i32_16x16x64_i8 v[126:129], v[70:73], v[200:203], v[126:129]
	v_mfma_i32_16x16x64_i8 v[122:125], v[78:81], v[200:203], v[122:125]
	v_mfma_i32_16x16x64_i8 v[110:113], v[70:73], v[208:211], v[110:113]
	v_mfma_i32_16x16x64_i8 v[106:109], v[78:81], v[208:211], v[106:109]
	v_mfma_i32_16x16x64_i8 v[94:97], v[70:73], v[216:219], v[94:97]
	v_mfma_i32_16x16x64_i8 v[90:93], v[78:81], v[216:219], v[90:93]
	v_mfma_i32_16x16x64_i8 v[134:137], v[146:149], v[188:191], v[134:137]
	v_mfma_i32_16x16x64_i8 v[130:133], v[174:177], v[188:191], v[130:133]
	v_mfma_i32_16x16x64_i8 v[118:121], v[146:149], v[196:199], v[118:121]
	v_mfma_i32_16x16x64_i8 v[114:117], v[174:177], v[196:199], v[114:117]
	v_mfma_i32_16x16x64_i8 v[102:105], v[146:149], v[204:207], v[102:105]
	v_mfma_i32_16x16x64_i8 v[98:101], v[174:177], v[204:207], v[98:101]
	v_mfma_i32_16x16x64_i8 v[86:89], v[146:149], v[212:215], v[86:89]
	v_mfma_i32_16x16x64_i8 v[82:85], v[174:177], v[212:215], v[82:85]
	v_mfma_i32_16x16x64_i8 v[134:137], v[150:153], v[192:195], v[134:137]
	v_mfma_i32_16x16x64_i8 v[130:133], v[184:187], v[192:195], v[130:133]
	v_mfma_i32_16x16x64_i8 v[118:121], v[150:153], v[200:203], v[118:121]
	v_mfma_i32_16x16x64_i8 v[114:117], v[184:187], v[200:203], v[114:117]
	v_mfma_i32_16x16x64_i8 v[102:105], v[150:153], v[208:211], v[102:105]
	v_mfma_i32_16x16x64_i8 v[98:101], v[184:187], v[208:211], v[98:101]
	v_mfma_i32_16x16x64_i8 v[86:89], v[150:153], v[216:219], v[86:89]
	v_mfma_i32_16x16x64_i8 v[82:85], v[184:187], v[216:219], v[82:85]
	s_barrier
	s_setprio 1
	s_add_i32 s50, s41, s30
	s_mov_b32 m0, s50
	ds_read_b128 v[188:191], v182 offset:16384
	ds_read_b128 v[192:195], v182 offset:17408
	ds_read_b128 v[196:199], v182 offset:18432
	ds_read_b128 v[200:203], v182 offset:19456
	ds_read_b128 v[204:207], v182 offset:20480
	ds_read_b128 v[208:211], v182 offset:21504
	ds_read_b128 v[212:215], v182 offset:22528
	ds_read_b128 v[216:219], v182 offset:23552
	global_load_lds_dwordx4 v158, s[22:23]
	s_add_i32 m0, s50, 0x2000
	s_add_u32 s50, s22, 0x4000
	s_addc_u32 s51, s23, 0
	s_add_i32 s52, s42, s30
	global_load_lds_dwordx4 v162, s[22:23]
	s_mov_b32 m0, s52
	s_nop 0
	global_load_lds_dwordx4 v158, s[50:51]
	s_add_i32 m0, s52, 0x2000
	s_nop 0
	global_load_lds_dwordx4 v162, s[50:51]
	s_setprio 0
	s_waitcnt vmcnt(6)
	s_waitcnt lgkmcnt(0)
	s_barrier
	s_waitcnt lgkmcnt(0)
	v_mfma_i32_16x16x64_i8 v[62:65], v[66:69], v[188:191], v[62:65]
	v_mfma_i32_16x16x64_i8 v[58:61], v[74:77], v[188:191], v[58:61]
	v_mfma_i32_16x16x64_i8 v[46:49], v[66:69], v[196:199], v[46:49]
	v_mfma_i32_16x16x64_i8 v[42:45], v[74:77], v[196:199], v[42:45]
	v_mfma_i32_16x16x64_i8 v[30:33], v[66:69], v[204:207], v[30:33]
	v_mfma_i32_16x16x64_i8 v[26:29], v[74:77], v[204:207], v[26:29]
	v_mfma_i32_16x16x64_i8 v[14:17], v[66:69], v[212:215], v[14:17]
	v_mfma_i32_16x16x64_i8 v[10:13], v[74:77], v[212:215], v[10:13]
	v_mfma_i32_16x16x64_i8 v[62:65], v[70:73], v[192:195], v[62:65]
	v_mfma_i32_16x16x64_i8 v[58:61], v[78:81], v[192:195], v[58:61]
	v_mfma_i32_16x16x64_i8 v[46:49], v[70:73], v[200:203], v[46:49]
	v_mfma_i32_16x16x64_i8 v[42:45], v[78:81], v[200:203], v[42:45]
	v_mfma_i32_16x16x64_i8 v[30:33], v[70:73], v[208:211], v[30:33]
	v_mfma_i32_16x16x64_i8 v[26:29], v[78:81], v[208:211], v[26:29]
	v_mfma_i32_16x16x64_i8 v[14:17], v[70:73], v[216:219], v[14:17]
	v_mfma_i32_16x16x64_i8 v[10:13], v[78:81], v[216:219], v[10:13]
	v_mfma_i32_16x16x64_i8 v[54:57], v[146:149], v[188:191], v[54:57]
	v_mfma_i32_16x16x64_i8 v[50:53], v[174:177], v[188:191], v[50:53]
	v_mfma_i32_16x16x64_i8 v[38:41], v[146:149], v[196:199], v[38:41]
	v_mfma_i32_16x16x64_i8 v[34:37], v[174:177], v[196:199], v[34:37]
	v_mfma_i32_16x16x64_i8 v[22:25], v[146:149], v[204:207], v[22:25]
	v_mfma_i32_16x16x64_i8 v[18:21], v[174:177], v[204:207], v[18:21]
	v_mfma_i32_16x16x64_i8 v[6:9], v[146:149], v[212:215], v[6:9]
	v_mfma_i32_16x16x64_i8 v[2:5], v[174:177], v[212:215], v[2:5]
	v_mfma_i32_16x16x64_i8 v[54:57], v[150:153], v[192:195], v[54:57]
	v_mfma_i32_16x16x64_i8 v[50:53], v[184:187], v[192:195], v[50:53]
	v_mfma_i32_16x16x64_i8 v[38:41], v[150:153], v[200:203], v[38:41]
	v_mfma_i32_16x16x64_i8 v[34:37], v[184:187], v[200:203], v[34:37]
	v_mfma_i32_16x16x64_i8 v[22:25], v[150:153], v[208:211], v[22:25]
	v_mfma_i32_16x16x64_i8 v[18:21], v[184:187], v[208:211], v[18:21]
	v_mfma_i32_16x16x64_i8 v[6:9], v[150:153], v[216:219], v[6:9]
	v_mfma_i32_16x16x64_i8 v[2:5], v[184:187], v[216:219], v[2:5]
	s_barrier
; #define PG8_STAGE(bufoff, gbase, voff) do { _Pragma("unroll") for (int _i = 0; _i < 2; ++_i) \
;         __builtin_amdgcn_global_load_lds((const unsigned*)((const char*)(gbase) + (voff)[_i]), (LAS unsigned*)(lds + (bufoff) + ldsw + _i * 8192), 16, 0, 0); } while (0)
; #define PG8_LDA(dst, b, h) do { _Pragma("unroll") for (int m = 0; m < 4; ++m) _Pragma("unroll") for (int k = 0; k < 2; ++k) dst[m][k] = *(const LAS bf16x8*)(lds + PG8_SA(b, h) + aoff + m * 2048 + k * 1024); } while (0)
; #define PG8_LDB(dst, b, h) do { _Pragma("unroll") for (int n = 0; n < 2; ++n) _Pragma("unroll") for (int k = 0; k < 2; ++k) dst[n][k] = *(const LAS bf16x8*)(lds + PG8_SB(b, h) + boff + n * 2048 + k * 1024); } while (0)
; #define PG8_WAIT_V(n) asm volatile("s_waitcnt vmcnt(" #n ")" ::: "memory")
; #define PG8_WAIT_L(n) asm volatile("s_waitcnt lgkmcnt(" #n ")" ::: "memory")
; #define PG8_BAR __builtin_amdgcn_s_barrier()
; #define PG8_SCHED __builtin_amdgcn_sched_barrier(0)
; template <class Epi, class Sched, bool I8 = false>
; __device__ __forceinline__ void gemm_phase(LAS unsigned char* lds, const Gemm g, const Sched& S, const Epi& E) {
;     ...
;         for (int t = 0; t < nt; t += 2) {
;             const bool last = (t == nt - 2);
;     ...
;             PG8_LDB(B0, 1, 0); PG8_LDB(B1, 1, 1); PG8_SCHED; PG8_LDA(At, 1, 0); PG8_STAGE(PG8_SA(0, 1), a2 + hstepA, voffA);
;             PG8_WAIT_V(8); PG8_WAIT_L(0); PG8_BAR; PG8_MMA(0, 0, At, B0); PG8_MMA(0, 1, At, B1); PG8_BAR; PG8_SCHED;
;             PG8_LDA(At, 1, 1); PG8_STAGE(PG8_SB(1, 0), b3, voffB); PG8_STAGE(PG8_SB(1, 1), b3 + hstepB, voffB); PG8_STAGE(PG8_SA(1, 0), a3, voffA);
;             PG8_WAIT_V(8); PG8_WAIT_L(0); PG8_BAR; PG8_MMA(1, 0, At, B0); PG8_MMA(1, 1, At, B1); PG8_BAR; PG8_SCHED;
	s_setprio 1
	s_add_i32 s50, 0, 0x18000
	s_add_i32 s51, 0, 0x1c000
	v_add_u32_e32 v78, s50, v178
	v_add_u32_e32 v164, s51, v178
	ds_read_b128 v[66:69], v78
	ds_read_b128 v[70:73], v78 offset:1024
	ds_read_b128 v[74:77], v78 offset:2048
	ds_read_b128 v[78:81], v78 offset:3072
	ds_read_b128 v[146:149], v164
	ds_read_b128 v[150:153], v164 offset:1024
	ds_read_b128 v[174:177], v164 offset:2048
	ds_read_b128 v[184:187], v164 offset:3072
	s_mov_b32 m0, s31
	s_nop 0
	global_load_lds_dwordx4 v156, s[24:25]
	s_mov_b32 m0, s33
	s_nop 0
	global_load_lds_dwordx4 v160, s[24:25]
	s_add_u32 s24, s24, 0x4000
	s_addc_u32 s25, s25, 0
	s_mov_b32 m0, s34
	ds_read_b128 v[188:191], v182 offset:32768
	ds_read_b128 v[192:195], v182 offset:33792
	ds_read_b128 v[196:199], v182 offset:34816
	ds_read_b128 v[200:203], v182 offset:35840
	ds_read_b128 v[204:207], v182 offset:36864
	ds_read_b128 v[208:211], v182 offset:37888
	ds_read_b128 v[212:215], v182 offset:38912
	ds_read_b128 v[216:219], v182 offset:39936
	global_load_lds_dwordx4 v156, s[24:25]
	s_mov_b32 m0, s35
	s_nop 0
	global_load_lds_dwordx4 v160, s[24:25]
	s_setprio 0
	s_waitcnt vmcnt(8)
	s_waitcnt lgkmcnt(0)
	s_barrier
	s_waitcnt lgkmcnt(0)
	v_mfma_i32_16x16x64_i8 v[142:145], v[66:69], v[188:191], v[142:145]
	v_mfma_i32_16x16x64_i8 v[138:141], v[74:77], v[188:191], v[138:141]
	v_mfma_i32_16x16x64_i8 v[126:129], v[66:69], v[196:199], v[126:129]
	v_mfma_i32_16x16x64_i8 v[122:125], v[74:77], v[196:199], v[122:125]
	v_mfma_i32_16x16x64_i8 v[110:113], v[66:69], v[204:207], v[110:113]
	v_mfma_i32_16x16x64_i8 v[106:109], v[74:77], v[204:207], v[106:109]
	v_mfma_i32_16x16x64_i8 v[94:97], v[66:69], v[212:215], v[94:97]
	v_mfma_i32_16x16x64_i8 v[90:93], v[74:77], v[212:215], v[90:93]
	v_mfma_i32_16x16x64_i8 v[142:145], v[70:73], v[192:195], v[142:145]
	v_mfma_i32_16x16x64_i8 v[138:141], v[78:81], v[192:195], v[138:141]
	v_mfma_i32_16x16x64_i8 v[126:129], v[70:73], v[200:203], v[126:129]
	v_mfma_i32_16x16x64_i8 v[122:125], v[78:81], v[200:203], v[122:125]
	v_mfma_i32_16x16x64_i8 v[110:113], v[70:73], v[208:211], v[110:113]
	v_mfma_i32_16x16x64_i8 v[106:109], v[78:81], v[208:211], v[106:109]
	v_mfma_i32_16x16x64_i8 v[94:97], v[70:73], v[216:219], v[94:97]
	v_mfma_i32_16x16x64_i8 v[90:93], v[78:81], v[216:219], v[90:93]
	v_mfma_i32_16x16x64_i8 v[134:137], v[146:149], v[188:191], v[134:137]
	v_mfma_i32_16x16x64_i8 v[130:133], v[174:177], v[188:191], v[130:133]
	v_mfma_i32_16x16x64_i8 v[118:121], v[146:149], v[196:199], v[118:121]
	v_mfma_i32_16x16x64_i8 v[114:117], v[174:177], v[196:199], v[114:117]
	v_mfma_i32_16x16x64_i8 v[102:105], v[146:149], v[204:207], v[102:105]
	v_mfma_i32_16x16x64_i8 v[98:101], v[174:177], v[204:207], v[98:101]
	v_mfma_i32_16x16x64_i8 v[86:89], v[146:149], v[212:215], v[86:89]
	v_mfma_i32_16x16x64_i8 v[82:85], v[174:177], v[212:215], v[82:85]
	v_mfma_i32_16x16x64_i8 v[134:137], v[150:153], v[192:195], v[134:137]
	v_mfma_i32_16x16x64_i8 v[130:133], v[184:187], v[192:195], v[130:133]
	v_mfma_i32_16x16x64_i8 v[118:121], v[150:153], v[200:203], v[118:121]
	v_mfma_i32_16x16x64_i8 v[114:117], v[184:187], v[200:203], v[114:117]
	v_mfma_i32_16x16x64_i8 v[102:105], v[150:153], v[208:211], v[102:105]
	v_mfma_i32_16x16x64_i8 v[98:101], v[184:187], v[208:211], v[98:101]
	v_mfma_i32_16x16x64_i8 v[86:89], v[150:153], v[216:219], v[86:89]
	v_mfma_i32_16x16x64_i8 v[82:85], v[184:187], v[216:219], v[82:85]
	s_barrier
	s_setprio 1
	s_add_u32 s24, s22, 0x8000
	s_addc_u32 s25, s23, 0
	s_add_i32 s50, s50, s30
	s_mov_b32 m0, s50
	ds_read_b128 v[188:191], v182 offset:49152
	ds_read_b128 v[192:195], v182 offset:50176
	ds_read_b128 v[196:199], v182 offset:51200
	ds_read_b128 v[200:203], v182 offset:52224
	ds_read_b128 v[204:207], v182 offset:53248
	ds_read_b128 v[208:211], v182 offset:54272
	ds_read_b128 v[212:215], v182 offset:55296
	ds_read_b128 v[216:219], v182 offset:56320
	global_load_lds_dwordx4 v158, s[24:25]
	s_add_i32 m0, s50, 0x2000
	s_add_u32 s22, s22, 0xc000
	v_lshl_add_u64 v[220:221], s[24:25], 0, v[162:163]
	s_addc_u32 s23, s23, 0
	s_add_i32 s24, s51, s30
	global_load_lds_dwordx4 v[220:221], off
	s_mov_b32 m0, s24
	s_nop 0
	global_load_lds_dwordx4 v158, s[22:23]
	s_add_i32 m0, s24, 0x2000
	s_nop 0
	global_load_lds_dwordx4 v162, s[22:23]
	s_setprio 0
	s_waitcnt vmcnt(6)
	s_waitcnt lgkmcnt(0)
	s_barrier
	s_waitcnt lgkmcnt(0)
	v_mfma_i32_16x16x64_i8 v[62:65], v[66:69], v[188:191], v[62:65]
	v_mfma_i32_16x16x64_i8 v[58:61], v[74:77], v[188:191], v[58:61]
	v_mfma_i32_16x16x64_i8 v[46:49], v[66:69], v[196:199], v[46:49]
	v_mfma_i32_16x16x64_i8 v[42:45], v[74:77], v[196:199], v[42:45]
	v_mfma_i32_16x16x64_i8 v[30:33], v[66:69], v[204:207], v[30:33]
	v_mfma_i32_16x16x64_i8 v[26:29], v[74:77], v[204:207], v[26:29]
	v_mfma_i32_16x16x64_i8 v[14:17], v[66:69], v[212:215], v[14:17]
	v_mfma_i32_16x16x64_i8 v[10:13], v[74:77], v[212:215], v[10:13]
	v_mfma_i32_16x16x64_i8 v[62:65], v[70:73], v[192:195], v[62:65]
	v_mfma_i32_16x16x64_i8 v[58:61], v[78:81], v[192:195], v[58:61]
	v_mfma_i32_16x16x64_i8 v[46:49], v[70:73], v[200:203], v[46:49]
	v_mfma_i32_16x16x64_i8 v[42:45], v[78:81], v[200:203], v[42:45]
	v_mfma_i32_16x16x64_i8 v[30:33], v[70:73], v[208:211], v[30:33]
	v_mfma_i32_16x16x64_i8 v[26:29], v[78:81], v[208:211], v[26:29]
	v_mfma_i32_16x16x64_i8 v[14:17], v[70:73], v[216:219], v[14:17]
	v_mfma_i32_16x16x64_i8 v[10:13], v[78:81], v[216:219], v[10:13]
	v_mfma_i32_16x16x64_i8 v[54:57], v[146:149], v[188:191], v[54:57]
	v_mfma_i32_16x16x64_i8 v[50:53], v[174:177], v[188:191], v[50:53]
	v_mfma_i32_16x16x64_i8 v[38:41], v[146:149], v[196:199], v[38:41]
	v_mfma_i32_16x16x64_i8 v[34:37], v[174:177], v[196:199], v[34:37]
	v_mfma_i32_16x16x64_i8 v[22:25], v[146:149], v[204:207], v[22:25]
	v_mfma_i32_16x16x64_i8 v[18:21], v[174:177], v[204:207], v[18:21]
	v_mfma_i32_16x16x64_i8 v[6:9], v[146:149], v[212:215], v[6:9]
	v_mfma_i32_16x16x64_i8 v[2:5], v[174:177], v[212:215], v[2:5]
	v_mfma_i32_16x16x64_i8 v[54:57], v[150:153], v[192:195], v[54:57]
	v_mfma_i32_16x16x64_i8 v[50:53], v[184:187], v[192:195], v[50:53]
	v_mfma_i32_16x16x64_i8 v[38:41], v[150:153], v[200:203], v[38:41]
	v_mfma_i32_16x16x64_i8 v[34:37], v[184:187], v[200:203], v[34:37]
	v_mfma_i32_16x16x64_i8 v[22:25], v[150:153], v[208:211], v[22:25]
	v_mfma_i32_16x16x64_i8 v[18:21], v[184:187], v[208:211], v[18:21]
	v_mfma_i32_16x16x64_i8 v[6:9], v[150:153], v[216:219], v[6:9]
	v_mfma_i32_16x16x64_i8 v[2:5], v[184:187], v[216:219], v[2:5]
	s_barrier
	s_add_i32 s49, s49, 2
	s_add_u32 s18, s18, 0x10000
	s_addc_u32 s19, s19, 0
	s_add_u32 s47, s47, 0x10000
	s_addc_u32 s48, s48, 0
	s_cmpk_gt_u32 s49, 0x53
	s_cbranch_scc0 .LBB0_1393
	s_and_b64 vcc, exec, s[14:15]
	s_cbranch_vccz .LBB0_1396
	s_barrier

; #define PG8_STAGE(bufoff, gbase, voff) do { _Pragma("unroll") for (int _i = 0; _i < 2; ++_i) \
;         __builtin_amdgcn_global_load_lds((const unsigned*)((const char*)(gbase) + (voff)[_i]), (LAS unsigned*)(lds + (bufoff) + ldsw + _i * 8192), 16, 0, 0); } while (0)
; #define PG8_LDA(dst, b, h) do { _Pragma("unroll") for (int m = 0; m < 4; ++m) _Pragma("unroll") for (int k = 0; k < 2; ++k) dst[m][k] = *(const LAS bf16x8*)(lds + PG8_SA(b, h) + aoff + m * 2048 + k * 1024); } while (0)
; #define PG8_LDB(dst, b, h) do { _Pragma("unroll") for (int n = 0; n < 2; ++n) _Pragma("unroll") for (int k = 0; k < 2; ++k) dst[n][k] = *(const LAS bf16x8*)(lds + PG8_SB(b, h) + boff + n * 2048 + k * 1024); } while (0)
; #define PG8_WAIT_V(n) asm volatile("s_waitcnt vmcnt(" #n ")" ::: "memory")
; #define PG8_WAIT_L(n) asm volatile("s_waitcnt lgkmcnt(" #n ")" ::: "memory")
; #define PG8_BAR __builtin_amdgcn_s_barrier()
; #define PG8_SCHED __builtin_amdgcn_sched_barrier(0)
; template <class Epi, class Sched, bool I8 = false>
; __device__ __forceinline__ void gemm_phase(LAS unsigned char* lds, const Gemm g, const Sched& S, const Epi& E) {
;     ...
;             PG8_LDB(B0, 0, 0); PG8_LDB(B1, 0, 1); PG8_SCHED; PG8_LDA(At, 0, 0); PG8_STAGE(PG8_SA(1, 1), a1 + hstepA, voffA);
;             PG8_WAIT_V(8); PG8_WAIT_L(0); PG8_BAR; PG8_MMA(0, 0, At, B0); PG8_MMA(0, 1, At, B1); PG8_BAR; PG8_SCHED;
;             PG8_LDA(At, 0, 1); PG8_STAGE(PG8_SB(0, 0), b2, voffB); PG8_STAGE(PG8_SB(0, 1), b2 + hstepB, voffB); PG8_STAGE(PG8_SA(0, 0), a2, voffA);
;             PG8_WAIT_V(8); PG8_WAIT_L(0); PG8_BAR; PG8_MMA(1, 0, At, B0); PG8_MMA(1, 1, At, B1); PG8_BAR; PG8_SCHED;
.LBB0_1482:
	s_setprio 1
	ds_read_b128 v[152:155], v182
	ds_read_b128 v[156:159], v182 offset:1024
	ds_read_b128 v[160:163], v182 offset:2048
	ds_read_b128 v[164:167], v182 offset:3072
	ds_read_b128 v[168:171], v183
	ds_read_b128 v[172:175], v183 offset:1024
	ds_read_b128 v[176:179], v183 offset:2048
	ds_read_b128 v[186:189], v183 offset:3072
	s_add_u32 s38, s8, 0x4000
	s_addc_u32 s39, s9, 0
	s_cmp_eq_u32 s47, 60
	s_cselect_b32 s42, s31, s38
	s_cselect_b32 s43, s7, s39
	s_cselect_b32 s40, s44, s45
	s_cselect_b32 s41, s29, s46
	s_add_u32 s38, s42, 0x8000
	s_addc_u32 s39, s43, 0
	s_sub_u32 s98, s8, 0x4000
	s_subb_u32 s99, s9, 0
	s_mov_b32 m0, s58
	s_nop 0
	global_load_lds_dwordx4 v130, s[98:99]
	s_mov_b32 m0, s59
	s_nop 0
	global_load_lds_dwordx4 v134, s[98:99]
	s_add_i32 m0, s33, 0xc000
	ds_read_b128 v[190:193], v184
	ds_read_b128 v[194:197], v184 offset:1024
	ds_read_b128 v[198:201], v184 offset:2048
	ds_read_b128 v[202:205], v184 offset:3072
	ds_read_b128 v[206:209], v184 offset:4096
	ds_read_b128 v[210:213], v184 offset:5120
	ds_read_b128 v[214:217], v184 offset:6144
	ds_read_b128 v[218:221], v184 offset:7168
	global_load_lds_dwordx4 v144, s[8:9]
	s_add_i32 m0, s33, 0xe000
	s_nop 0
	global_load_lds_dwordx4 v146, s[8:9]
	s_setprio 0
	s_waitcnt vmcnt(8)
	s_waitcnt lgkmcnt(0)
	s_barrier
	s_waitcnt lgkmcnt(0)
	v_mfma_f32_16x16x32_bf16 v[126:129], v[152:155], v[190:193], v[126:129]
	v_mfma_f32_16x16x32_bf16 v[122:125], v[160:163], v[190:193], v[122:125]
	v_mfma_f32_16x16x32_bf16 v[110:113], v[152:155], v[198:201], v[110:113]
	v_mfma_f32_16x16x32_bf16 v[106:109], v[160:163], v[198:201], v[106:109]
	v_mfma_f32_16x16x32_bf16 v[94:97], v[152:155], v[206:209], v[94:97]
	v_mfma_f32_16x16x32_bf16 v[90:93], v[160:163], v[206:209], v[90:93]
	v_mfma_f32_16x16x32_bf16 v[78:81], v[152:155], v[214:217], v[78:81]
	v_mfma_f32_16x16x32_bf16 v[74:77], v[160:163], v[214:217], v[74:77]
	v_mfma_f32_16x16x32_bf16 v[126:129], v[156:159], v[194:197], v[126:129]
	v_mfma_f32_16x16x32_bf16 v[122:125], v[164:167], v[194:197], v[122:125]
	v_mfma_f32_16x16x32_bf16 v[110:113], v[156:159], v[202:205], v[110:113]
	v_mfma_f32_16x16x32_bf16 v[106:109], v[164:167], v[202:205], v[106:109]
	v_mfma_f32_16x16x32_bf16 v[94:97], v[156:159], v[210:213], v[94:97]
	v_mfma_f32_16x16x32_bf16 v[90:93], v[164:167], v[210:213], v[90:93]
	v_mfma_f32_16x16x32_bf16 v[78:81], v[156:159], v[218:221], v[78:81]
	v_mfma_f32_16x16x32_bf16 v[74:77], v[164:167], v[218:221], v[74:77]
	v_mfma_f32_16x16x32_bf16 v[118:121], v[168:171], v[190:193], v[118:121]
	v_mfma_f32_16x16x32_bf16 v[114:117], v[176:179], v[190:193], v[114:117]
	v_mfma_f32_16x16x32_bf16 v[102:105], v[168:171], v[198:201], v[102:105]
	v_mfma_f32_16x16x32_bf16 v[98:101], v[176:179], v[198:201], v[98:101]
	v_mfma_f32_16x16x32_bf16 v[86:89], v[168:171], v[206:209], v[86:89]
	v_mfma_f32_16x16x32_bf16 v[82:85], v[176:179], v[206:209], v[82:85]
	v_mfma_f32_16x16x32_bf16 v[70:73], v[168:171], v[214:217], v[70:73]
	v_mfma_f32_16x16x32_bf16 v[66:69], v[176:179], v[214:217], v[66:69]
	v_mfma_f32_16x16x32_bf16 v[118:121], v[172:175], v[194:197], v[118:121]
	v_mfma_f32_16x16x32_bf16 v[114:117], v[186:189], v[194:197], v[114:117]
	v_mfma_f32_16x16x32_bf16 v[102:105], v[172:175], v[202:205], v[102:105]
	v_mfma_f32_16x16x32_bf16 v[98:101], v[186:189], v[202:205], v[98:101]
	v_mfma_f32_16x16x32_bf16 v[86:89], v[172:175], v[210:213], v[86:89]
	v_mfma_f32_16x16x32_bf16 v[82:85], v[186:189], v[210:213], v[82:85]
	v_mfma_f32_16x16x32_bf16 v[70:73], v[172:175], v[218:221], v[70:73]
	v_mfma_f32_16x16x32_bf16 v[66:69], v[186:189], v[218:221], v[66:69]
	s_barrier
	s_setprio 1
	s_add_i32 s48, s63, s25
	s_mov_b32 m0, s48
	ds_read_b128 v[190:193], v184 offset:16384
	ds_read_b128 v[194:197], v184 offset:17408
	ds_read_b128 v[198:201], v184 offset:18432
	ds_read_b128 v[202:205], v184 offset:19456
	ds_read_b128 v[206:209], v184 offset:20480
	ds_read_b128 v[210:213], v184 offset:21504
	ds_read_b128 v[214:217], v184 offset:22528
	ds_read_b128 v[218:221], v184 offset:23552
	global_load_lds_dwordx4 v132, s[40:41]
	s_add_i32 m0, s48, 0x2000
	s_add_u32 s48, s40, 0x4000
	s_addc_u32 s49, s41, 0
	s_add_i32 s50, s64, s25
	global_load_lds_dwordx4 v136, s[40:41]
	s_mov_b32 m0, s50
	s_nop 0
	global_load_lds_dwordx4 v132, s[48:49]
	s_add_i32 m0, s50, 0x2000
	s_nop 0
	global_load_lds_dwordx4 v136, s[48:49]
	s_setprio 0
	s_waitcnt vmcnt(6)
	s_waitcnt lgkmcnt(0)
	s_barrier
	s_waitcnt lgkmcnt(0)
	v_mfma_f32_16x16x32_bf16 v[62:65], v[152:155], v[190:193], v[62:65]
	v_mfma_f32_16x16x32_bf16 v[58:61], v[160:163], v[190:193], v[58:61]
	v_mfma_f32_16x16x32_bf16 v[46:49], v[152:155], v[198:201], v[46:49]
	v_mfma_f32_16x16x32_bf16 v[42:45], v[160:163], v[198:201], v[42:45]
	v_mfma_f32_16x16x32_bf16 v[30:33], v[152:155], v[206:209], v[30:33]
	v_mfma_f32_16x16x32_bf16 v[26:29], v[160:163], v[206:209], v[26:29]
	v_mfma_f32_16x16x32_bf16 v[14:17], v[152:155], v[214:217], v[14:17]
	v_mfma_f32_16x16x32_bf16 v[10:13], v[160:163], v[214:217], v[10:13]
	v_mfma_f32_16x16x32_bf16 v[62:65], v[156:159], v[194:197], v[62:65]
	v_mfma_f32_16x16x32_bf16 v[58:61], v[164:167], v[194:197], v[58:61]
	v_mfma_f32_16x16x32_bf16 v[46:49], v[156:159], v[202:205], v[46:49]
	v_mfma_f32_16x16x32_bf16 v[42:45], v[164:167], v[202:205], v[42:45]
	v_mfma_f32_16x16x32_bf16 v[30:33], v[156:159], v[210:213], v[30:33]
	v_mfma_f32_16x16x32_bf16 v[26:29], v[164:167], v[210:213], v[26:29]
	v_mfma_f32_16x16x32_bf16 v[14:17], v[156:159], v[218:221], v[14:17]
	v_mfma_f32_16x16x32_bf16 v[10:13], v[164:167], v[218:221], v[10:13]
	v_mfma_f32_16x16x32_bf16 v[54:57], v[168:171], v[190:193], v[54:57]
	v_mfma_f32_16x16x32_bf16 v[50:53], v[176:179], v[190:193], v[50:53]
	v_mfma_f32_16x16x32_bf16 v[38:41], v[168:171], v[198:201], v[38:41]
	v_mfma_f32_16x16x32_bf16 v[34:37], v[176:179], v[198:201], v[34:37]
	v_mfma_f32_16x16x32_bf16 v[22:25], v[168:171], v[206:209], v[22:25]
	v_mfma_f32_16x16x32_bf16 v[18:21], v[176:179], v[206:209], v[18:21]
	v_mfma_f32_16x16x32_bf16 v[6:9], v[168:171], v[214:217], v[6:9]
	v_mfma_f32_16x16x32_bf16 v[2:5], v[176:179], v[214:217], v[2:5]
	v_mfma_f32_16x16x32_bf16 v[54:57], v[172:175], v[194:197], v[54:57]
	v_mfma_f32_16x16x32_bf16 v[50:53], v[186:189], v[194:197], v[50:53]
	v_mfma_f32_16x16x32_bf16 v[38:41], v[172:175], v[202:205], v[38:41]
	v_mfma_f32_16x16x32_bf16 v[34:37], v[186:189], v[202:205], v[34:37]
	v_mfma_f32_16x16x32_bf16 v[22:25], v[172:175], v[210:213], v[22:25]
	v_mfma_f32_16x16x32_bf16 v[18:21], v[186:189], v[210:213], v[18:21]
	v_mfma_f32_16x16x32_bf16 v[6:9], v[172:175], v[218:221], v[6:9]
	v_mfma_f32_16x16x32_bf16 v[2:5], v[186:189], v[218:221], v[2:5]
	s_barrier
; #define PG8_STAGE(bufoff, gbase, voff) do { _Pragma("unroll") for (int _i = 0; _i < 2; ++_i) \
;         __builtin_amdgcn_global_load_lds((const unsigned*)((const char*)(gbase) + (voff)[_i]), (LAS unsigned*)(lds + (bufoff) + ldsw + _i * 8192), 16, 0, 0); } while (0)
; #define PG8_LDA(dst, b, h) do { _Pragma("unroll") for (int m = 0; m < 4; ++m) _Pragma("unroll") for (int k = 0; k < 2; ++k) dst[m][k] = *(const LAS bf16x8*)(lds + PG8_SA(b, h) + aoff + m * 2048 + k * 1024); } while (0)
; #define PG8_LDB(dst, b, h) do { _Pragma("unroll") for (int n = 0; n < 2; ++n) _Pragma("unroll") for (int k = 0; k < 2; ++k) dst[n][k] = *(const LAS bf16x8*)(lds + PG8_SB(b, h) + boff + n * 2048 + k * 1024); } while (0)
; #define PG8_WAIT_V(n) asm volatile("s_waitcnt vmcnt(" #n ")" ::: "memory")
; #define PG8_WAIT_L(n) asm volatile("s_waitcnt lgkmcnt(" #n ")" ::: "memory")
; #define PG8_BAR __builtin_amdgcn_s_barrier()
; #define PG8_SCHED __builtin_amdgcn_sched_barrier(0)
; template <class Epi, class Sched, bool I8 = false>
; __device__ __forceinline__ void gemm_phase(LAS unsigned char* lds, const Gemm g, const Sched& S, const Epi& E) {
;     ...
;         for (int t = 0; t < nt; t += 2) {
;             const bool last = (t == nt - 2);
;     ...
;             PG8_LDB(B0, 1, 0); PG8_LDB(B1, 1, 1); PG8_SCHED; PG8_LDA(At, 1, 0); PG8_STAGE(PG8_SA(0, 1), a2 + hstepA, voffA);
;             PG8_WAIT_V(8); PG8_WAIT_L(0); PG8_BAR; PG8_MMA(0, 0, At, B0); PG8_MMA(0, 1, At, B1); PG8_BAR; PG8_SCHED;
;             PG8_LDA(At, 1, 1); PG8_STAGE(PG8_SB(1, 0), b3, voffB); PG8_STAGE(PG8_SB(1, 1), b3 + hstepB, voffB); PG8_STAGE(PG8_SA(1, 0), a3, voffA);
;             PG8_WAIT_V(8); PG8_WAIT_L(0); PG8_BAR; PG8_MMA(1, 0, At, B0); PG8_MMA(1, 1, At, B1); PG8_BAR; PG8_SCHED;
	s_setprio 1
	s_add_i32 s48, 0, 0x18000
	v_add_u32_e32 v138, s48, v181
	s_add_i32 s49, 0, 0x1c000
	ds_read_b128 v[152:155], v138
	ds_read_b128 v[156:159], v138 offset:1024
	ds_read_b128 v[160:163], v138 offset:2048
	ds_read_b128 v[164:167], v138 offset:3072
	v_add_u32_e32 v138, s49, v181
	ds_read_b128 v[168:171], v138
	ds_read_b128 v[172:175], v138 offset:1024
	ds_read_b128 v[176:179], v138 offset:2048
	ds_read_b128 v[186:189], v138 offset:3072
	s_mov_b32 m0, s33
	s_nop 0
	global_load_lds_dwordx4 v130, s[42:43]
	s_mov_b32 m0, s52
	s_nop 0
	global_load_lds_dwordx4 v134, s[42:43]
	s_add_u32 s42, s42, 0x4000
	s_addc_u32 s43, s43, 0
	s_mov_b32 m0, s53
	ds_read_b128 v[190:193], v184 offset:32768
	ds_read_b128 v[194:197], v184 offset:33792
	ds_read_b128 v[198:201], v184 offset:34816
	ds_read_b128 v[202:205], v184 offset:35840
	ds_read_b128 v[206:209], v184 offset:36864
	ds_read_b128 v[210:213], v184 offset:37888
	ds_read_b128 v[214:217], v184 offset:38912
	ds_read_b128 v[218:221], v184 offset:39936
	global_load_lds_dwordx4 v130, s[42:43]
	s_mov_b32 m0, s54
	s_nop 0
	global_load_lds_dwordx4 v134, s[42:43]
	s_setprio 0
	s_waitcnt vmcnt(8)
	s_waitcnt lgkmcnt(0)
	s_barrier
	s_waitcnt lgkmcnt(0)
	v_mfma_f32_16x16x32_bf16 v[126:129], v[152:155], v[190:193], v[126:129]
	v_mfma_f32_16x16x32_bf16 v[122:125], v[160:163], v[190:193], v[122:125]
	v_mfma_f32_16x16x32_bf16 v[110:113], v[152:155], v[198:201], v[110:113]
	v_mfma_f32_16x16x32_bf16 v[106:109], v[160:163], v[198:201], v[106:109]
	v_mfma_f32_16x16x32_bf16 v[94:97], v[152:155], v[206:209], v[94:97]
	v_mfma_f32_16x16x32_bf16 v[90:93], v[160:163], v[206:209], v[90:93]
	v_mfma_f32_16x16x32_bf16 v[78:81], v[152:155], v[214:217], v[78:81]
	v_mfma_f32_16x16x32_bf16 v[74:77], v[160:163], v[214:217], v[74:77]
	v_mfma_f32_16x16x32_bf16 v[126:129], v[156:159], v[194:197], v[126:129]
	v_mfma_f32_16x16x32_bf16 v[122:125], v[164:167], v[194:197], v[122:125]
	v_mfma_f32_16x16x32_bf16 v[110:113], v[156:159], v[202:205], v[110:113]
	v_mfma_f32_16x16x32_bf16 v[106:109], v[164:167], v[202:205], v[106:109]
	v_mfma_f32_16x16x32_bf16 v[94:97], v[156:159], v[210:213], v[94:97]
	v_mfma_f32_16x16x32_bf16 v[90:93], v[164:167], v[210:213], v[90:93]
	v_mfma_f32_16x16x32_bf16 v[78:81], v[156:159], v[218:221], v[78:81]
	v_mfma_f32_16x16x32_bf16 v[74:77], v[164:167], v[218:221], v[74:77]
	v_mfma_f32_16x16x32_bf16 v[118:121], v[168:171], v[190:193], v[118:121]
	v_mfma_f32_16x16x32_bf16 v[114:117], v[176:179], v[190:193], v[114:117]
	v_mfma_f32_16x16x32_bf16 v[102:105], v[168:171], v[198:201], v[102:105]
	v_mfma_f32_16x16x32_bf16 v[98:101], v[176:179], v[198:201], v[98:101]
	v_mfma_f32_16x16x32_bf16 v[86:89], v[168:171], v[206:209], v[86:89]
	v_mfma_f32_16x16x32_bf16 v[82:85], v[176:179], v[206:209], v[82:85]
	v_mfma_f32_16x16x32_bf16 v[70:73], v[168:171], v[214:217], v[70:73]
	v_mfma_f32_16x16x32_bf16 v[66:69], v[176:179], v[214:217], v[66:69]
	v_mfma_f32_16x16x32_bf16 v[118:121], v[172:175], v[194:197], v[118:121]
	v_mfma_f32_16x16x32_bf16 v[114:117], v[186:189], v[194:197], v[114:117]
	v_mfma_f32_16x16x32_bf16 v[102:105], v[172:175], v[202:205], v[102:105]
	v_mfma_f32_16x16x32_bf16 v[98:101], v[186:189], v[202:205], v[98:101]
	v_mfma_f32_16x16x32_bf16 v[86:89], v[172:175], v[210:213], v[86:89]
	v_mfma_f32_16x16x32_bf16 v[82:85], v[186:189], v[210:213], v[82:85]
	v_mfma_f32_16x16x32_bf16 v[70:73], v[172:175], v[218:221], v[70:73]
	v_mfma_f32_16x16x32_bf16 v[66:69], v[186:189], v[218:221], v[66:69]
	s_barrier
	s_setprio 1
	s_add_u32 s42, s40, 0x8000
	s_addc_u32 s43, s41, 0
	s_add_i32 s48, s48, s25
	s_mov_b32 m0, s48
	ds_read_b128 v[190:193], v184 offset:49152
	ds_read_b128 v[194:197], v184 offset:50176
	ds_read_b128 v[198:201], v184 offset:51200
	ds_read_b128 v[202:205], v184 offset:52224
	ds_read_b128 v[206:209], v184 offset:53248
	ds_read_b128 v[210:213], v184 offset:54272
	ds_read_b128 v[214:217], v184 offset:55296
	ds_read_b128 v[218:221], v184 offset:56320
	global_load_lds_dwordx4 v132, s[42:43]
	s_add_i32 m0, s48, 0x2000
	s_add_u32 s40, s40, 0xc000
	v_lshl_add_u64 v[222:223], s[42:43], 0, v[136:137]
	s_addc_u32 s41, s41, 0
	s_add_i32 s42, s49, s25
	global_load_lds_dwordx4 v[222:223], off
	s_mov_b32 m0, s42
	s_nop 0
	global_load_lds_dwordx4 v132, s[40:41]
	s_add_i32 m0, s42, 0x2000
	s_nop 0
	global_load_lds_dwordx4 v136, s[40:41]
	s_setprio 0
	s_waitcnt vmcnt(6)
	s_waitcnt lgkmcnt(0)
	s_barrier
	s_waitcnt lgkmcnt(0)
	v_mfma_f32_16x16x32_bf16 v[62:65], v[152:155], v[190:193], v[62:65]
	v_mfma_f32_16x16x32_bf16 v[58:61], v[160:163], v[190:193], v[58:61]
	v_mfma_f32_16x16x32_bf16 v[46:49], v[152:155], v[198:201], v[46:49]
	v_mfma_f32_16x16x32_bf16 v[42:45], v[160:163], v[198:201], v[42:45]
	v_mfma_f32_16x16x32_bf16 v[30:33], v[152:155], v[206:209], v[30:33]
	v_mfma_f32_16x16x32_bf16 v[26:29], v[160:163], v[206:209], v[26:29]
	v_mfma_f32_16x16x32_bf16 v[14:17], v[152:155], v[214:217], v[14:17]
	v_mfma_f32_16x16x32_bf16 v[10:13], v[160:163], v[214:217], v[10:13]
	v_mfma_f32_16x16x32_bf16 v[62:65], v[156:159], v[194:197], v[62:65]
	v_mfma_f32_16x16x32_bf16 v[58:61], v[164:167], v[194:197], v[58:61]
	v_mfma_f32_16x16x32_bf16 v[46:49], v[156:159], v[202:205], v[46:49]
	v_mfma_f32_16x16x32_bf16 v[42:45], v[164:167], v[202:205], v[42:45]
	v_mfma_f32_16x16x32_bf16 v[30:33], v[156:159], v[210:213], v[30:33]
	v_mfma_f32_16x16x32_bf16 v[26:29], v[164:167], v[210:213], v[26:29]
	v_mfma_f32_16x16x32_bf16 v[14:17], v[156:159], v[218:221], v[14:17]
	v_mfma_f32_16x16x32_bf16 v[10:13], v[164:167], v[218:221], v[10:13]
	v_mfma_f32_16x16x32_bf16 v[54:57], v[168:171], v[190:193], v[54:57]
	v_mfma_f32_16x16x32_bf16 v[50:53], v[176:179], v[190:193], v[50:53]
	v_mfma_f32_16x16x32_bf16 v[38:41], v[168:171], v[198:201], v[38:41]
	v_mfma_f32_16x16x32_bf16 v[34:37], v[176:179], v[198:201], v[34:37]
	v_mfma_f32_16x16x32_bf16 v[22:25], v[168:171], v[206:209], v[22:25]
	v_mfma_f32_16x16x32_bf16 v[18:21], v[176:179], v[206:209], v[18:21]
	v_mfma_f32_16x16x32_bf16 v[6:9], v[168:171], v[214:217], v[6:9]
	v_mfma_f32_16x16x32_bf16 v[2:5], v[176:179], v[214:217], v[2:5]
	v_mfma_f32_16x16x32_bf16 v[54:57], v[172:175], v[194:197], v[54:57]
	v_mfma_f32_16x16x32_bf16 v[50:53], v[186:189], v[194:197], v[50:53]
	v_mfma_f32_16x16x32_bf16 v[38:41], v[172:175], v[202:205], v[38:41]
	v_mfma_f32_16x16x32_bf16 v[34:37], v[186:189], v[202:205], v[34:37]
	v_mfma_f32_16x16x32_bf16 v[22:25], v[172:175], v[210:213], v[22:25]
	v_mfma_f32_16x16x32_bf16 v[18:21], v[186:189], v[210:213], v[18:21]
	v_mfma_f32_16x16x32_bf16 v[6:9], v[172:175], v[218:221], v[6:9]
	v_mfma_f32_16x16x32_bf16 v[2:5], v[186:189], v[218:221], v[2:5]
	s_barrier
	s_add_i32 s47, s47, 2
	s_add_u32 s8, s8, 0x10000
	s_addc_u32 s9, s9, 0
	s_add_u32 s45, s45, 0x10000
	s_addc_u32 s46, s46, 0
	s_cmp_gt_u32 s47, 61
	s_cbranch_scc0 .LBB0_1482
	s_and_b64 vcc, exec, s[20:21]
	s_cbranch_vccz .LBB0_1485
	s_barrier

; #define PG8_STAGE(bufoff, gbase, voff) do { _Pragma("unroll") for (int _i = 0; _i < 2; ++_i) \
;         __builtin_amdgcn_global_load_lds((const unsigned*)((const char*)(gbase) + (voff)[_i]), (LAS unsigned*)(lds + (bufoff) + ldsw + _i * 8192), 16, 0, 0); } while (0)
; #define PG8_LDA(dst, b, h) do { _Pragma("unroll") for (int m = 0; m < 4; ++m) _Pragma("unroll") for (int k = 0; k < 2; ++k) dst[m][k] = *(const LAS bf16x8*)(lds + PG8_SA(b, h) + aoff + m * 2048 + k * 1024); } while (0)
; #define PG8_LDB(dst, b, h) do { _Pragma("unroll") for (int n = 0; n < 2; ++n) _Pragma("unroll") for (int k = 0; k < 2; ++k) dst[n][k] = *(const LAS bf16x8*)(lds + PG8_SB(b, h) + boff + n * 2048 + k * 1024); } while (0)
; #define PG8_WAIT_V(n) asm volatile("s_waitcnt vmcnt(" #n ")" ::: "memory")
; #define PG8_WAIT_L(n) asm volatile("s_waitcnt lgkmcnt(" #n ")" ::: "memory")
; #define PG8_BAR __builtin_amdgcn_s_barrier()
; #define PG8_SCHED __builtin_amdgcn_sched_barrier(0)
; template <class Epi, class Sched, bool I8 = false>
; __device__ __forceinline__ void gemm_phase(LAS unsigned char* lds, const Gemm g, const Sched& S, const Epi& E) {
;     ...
;             PG8_LDB(B0, 0, 0); PG8_LDB(B1, 0, 1); PG8_SCHED; PG8_LDA(At, 0, 0); PG8_STAGE(PG8_SA(1, 1), a1 + hstepA, voffA);
;             PG8_WAIT_V(8); PG8_WAIT_L(0); PG8_BAR; PG8_MMA(0, 0, At, B0); PG8_MMA(0, 1, At, B1); PG8_BAR; PG8_SCHED;
;             PG8_LDA(At, 0, 1); PG8_STAGE(PG8_SB(0, 0), b2, voffB); PG8_STAGE(PG8_SB(0, 1), b2 + hstepB, voffB); PG8_STAGE(PG8_SA(0, 0), a2, voffA);
;             PG8_WAIT_V(8); PG8_WAIT_L(0); PG8_BAR; PG8_MMA(1, 0, At, B0); PG8_MMA(1, 1, At, B1); PG8_BAR; PG8_SCHED;
.LBB0_2685:
	s_setprio 1
	ds_read_b128 v[130:133], v166
	ds_read_b128 v[134:137], v166 offset:1024
	ds_read_b128 v[158:161], v166 offset:2048
	ds_read_b128 v[170:173], v166 offset:3072
	ds_read_b128 v[174:177], v167
	ds_read_b128 v[178:181], v167 offset:1024
	ds_read_b128 v[182:185], v167 offset:2048
	ds_read_b128 v[186:189], v167 offset:3072
	s_add_u32 s12, s10, 0x4000
	s_addc_u32 s13, s11, 0
	s_cmp_eq_u32 s45, 4
	s_cselect_b32 s16, s40, s12
	s_cselect_b32 s17, s39, s13
	s_cselect_b32 s14, s42, s43
	s_cselect_b32 s15, s41, s44
	s_add_u32 s12, s16, 0x8000
	s_addc_u32 s13, s17, 0
	s_sub_u32 s98, s10, 0x4000
	s_subb_u32 s99, s11, 0
	s_mov_b32 m0, s33
	s_nop 0
	global_load_lds_dwordx4 v144, s[98:99]
	s_mov_b32 m0, s34
	s_nop 0
	global_load_lds_dwordx4 v140, s[98:99]
	s_add_i32 m0, s26, 0xc000
	ds_read_b128 v[190:193], v168
	ds_read_b128 v[194:197], v168 offset:1024
	ds_read_b128 v[198:201], v168 offset:2048
	ds_read_b128 v[202:205], v168 offset:3072
	ds_read_b128 v[206:209], v168 offset:4096
	ds_read_b128 v[210:213], v168 offset:5120
	ds_read_b128 v[214:217], v168 offset:6144
	ds_read_b128 v[218:221], v168 offset:7168
	global_load_lds_dwordx4 v150, s[10:11]
	s_add_i32 m0, s26, 0xe000
	s_nop 0
	global_load_lds_dwordx4 v152, s[10:11]
	s_setprio 0
	s_waitcnt vmcnt(8)
	s_waitcnt lgkmcnt(0)
	s_barrier
	s_waitcnt lgkmcnt(0)
	v_mfma_f32_16x16x32_bf16 v[126:129], v[130:133], v[190:193], v[126:129]
	v_mfma_f32_16x16x32_bf16 v[122:125], v[158:161], v[190:193], v[122:125]
	v_mfma_f32_16x16x32_bf16 v[118:121], v[130:133], v[198:201], v[118:121]
	v_mfma_f32_16x16x32_bf16 v[114:117], v[158:161], v[198:201], v[114:117]
	v_mfma_f32_16x16x32_bf16 v[110:113], v[130:133], v[206:209], v[110:113]
	v_mfma_f32_16x16x32_bf16 v[106:109], v[158:161], v[206:209], v[106:109]
	v_mfma_f32_16x16x32_bf16 v[102:105], v[130:133], v[214:217], v[102:105]
	v_mfma_f32_16x16x32_bf16 v[98:101], v[158:161], v[214:217], v[98:101]
	v_mfma_f32_16x16x32_bf16 v[126:129], v[134:137], v[194:197], v[126:129]
	v_mfma_f32_16x16x32_bf16 v[122:125], v[170:173], v[194:197], v[122:125]
	v_mfma_f32_16x16x32_bf16 v[118:121], v[134:137], v[202:205], v[118:121]
	v_mfma_f32_16x16x32_bf16 v[114:117], v[170:173], v[202:205], v[114:117]
	v_mfma_f32_16x16x32_bf16 v[110:113], v[134:137], v[210:213], v[110:113]
	v_mfma_f32_16x16x32_bf16 v[106:109], v[170:173], v[210:213], v[106:109]
	v_mfma_f32_16x16x32_bf16 v[102:105], v[134:137], v[218:221], v[102:105]
	v_mfma_f32_16x16x32_bf16 v[98:101], v[170:173], v[218:221], v[98:101]
	v_mfma_f32_16x16x32_bf16 v[62:65], v[174:177], v[190:193], v[62:65]
	v_mfma_f32_16x16x32_bf16 v[58:61], v[182:185], v[190:193], v[58:61]
	v_mfma_f32_16x16x32_bf16 v[54:57], v[174:177], v[198:201], v[54:57]
	v_mfma_f32_16x16x32_bf16 v[50:53], v[182:185], v[198:201], v[50:53]
	v_mfma_f32_16x16x32_bf16 v[46:49], v[174:177], v[206:209], v[46:49]
	v_mfma_f32_16x16x32_bf16 v[42:45], v[182:185], v[206:209], v[42:45]
	v_mfma_f32_16x16x32_bf16 v[38:41], v[174:177], v[214:217], v[38:41]
	v_mfma_f32_16x16x32_bf16 v[34:37], v[182:185], v[214:217], v[34:37]
	v_mfma_f32_16x16x32_bf16 v[62:65], v[178:181], v[194:197], v[62:65]
	v_mfma_f32_16x16x32_bf16 v[58:61], v[186:189], v[194:197], v[58:61]
	v_mfma_f32_16x16x32_bf16 v[54:57], v[178:181], v[202:205], v[54:57]
	v_mfma_f32_16x16x32_bf16 v[50:53], v[186:189], v[202:205], v[50:53]
	v_mfma_f32_16x16x32_bf16 v[46:49], v[178:181], v[210:213], v[46:49]
	v_mfma_f32_16x16x32_bf16 v[42:45], v[186:189], v[210:213], v[42:45]
	v_mfma_f32_16x16x32_bf16 v[38:41], v[178:181], v[218:221], v[38:41]
	v_mfma_f32_16x16x32_bf16 v[34:37], v[186:189], v[218:221], v[34:37]
	s_barrier
	s_setprio 1
	s_add_i32 s46, s62, s22
	s_mov_b32 m0, s46
	ds_read_b128 v[190:193], v168 offset:16384
	ds_read_b128 v[194:197], v168 offset:17408
	ds_read_b128 v[198:201], v168 offset:18432
	ds_read_b128 v[202:205], v168 offset:19456
	ds_read_b128 v[206:209], v168 offset:20480
	ds_read_b128 v[210:213], v168 offset:21504
	ds_read_b128 v[214:217], v168 offset:22528
	ds_read_b128 v[218:221], v168 offset:23552
	global_load_lds_dwordx4 v142, s[14:15]
	s_add_i32 m0, s46, 0x2000
	s_add_u32 s46, s14, 0x4000
	s_addc_u32 s47, s15, 0
	s_add_i32 s48, s35, s22
	global_load_lds_dwordx4 v138, s[14:15]
	s_mov_b32 m0, s48
	s_nop 0
	global_load_lds_dwordx4 v142, s[46:47]
	s_add_i32 m0, s48, 0x2000
	s_nop 0
	global_load_lds_dwordx4 v138, s[46:47]
	s_setprio 0
	s_waitcnt vmcnt(6)
	s_waitcnt lgkmcnt(0)
	s_barrier
	s_waitcnt lgkmcnt(0)
	v_mfma_f32_16x16x32_bf16 v[94:97], v[130:133], v[190:193], v[94:97]
	v_mfma_f32_16x16x32_bf16 v[90:93], v[158:161], v[190:193], v[90:93]
	v_mfma_f32_16x16x32_bf16 v[86:89], v[130:133], v[198:201], v[86:89]
	v_mfma_f32_16x16x32_bf16 v[82:85], v[158:161], v[198:201], v[82:85]
	v_mfma_f32_16x16x32_bf16 v[78:81], v[130:133], v[206:209], v[78:81]
	v_mfma_f32_16x16x32_bf16 v[74:77], v[158:161], v[206:209], v[74:77]
	v_mfma_f32_16x16x32_bf16 v[70:73], v[130:133], v[214:217], v[70:73]
	v_mfma_f32_16x16x32_bf16 v[66:69], v[158:161], v[214:217], v[66:69]
	v_mfma_f32_16x16x32_bf16 v[94:97], v[134:137], v[194:197], v[94:97]
	v_mfma_f32_16x16x32_bf16 v[90:93], v[170:173], v[194:197], v[90:93]
	v_mfma_f32_16x16x32_bf16 v[86:89], v[134:137], v[202:205], v[86:89]
	v_mfma_f32_16x16x32_bf16 v[82:85], v[170:173], v[202:205], v[82:85]
	v_mfma_f32_16x16x32_bf16 v[78:81], v[134:137], v[210:213], v[78:81]
	v_mfma_f32_16x16x32_bf16 v[74:77], v[170:173], v[210:213], v[74:77]
	v_mfma_f32_16x16x32_bf16 v[70:73], v[134:137], v[218:221], v[70:73]
	v_mfma_f32_16x16x32_bf16 v[66:69], v[170:173], v[218:221], v[66:69]
	v_mfma_f32_16x16x32_bf16 v[30:33], v[174:177], v[190:193], v[30:33]
	v_mfma_f32_16x16x32_bf16 v[26:29], v[182:185], v[190:193], v[26:29]
	v_mfma_f32_16x16x32_bf16 v[22:25], v[174:177], v[198:201], v[22:25]
	v_mfma_f32_16x16x32_bf16 v[18:21], v[182:185], v[198:201], v[18:21]
	v_mfma_f32_16x16x32_bf16 v[14:17], v[174:177], v[206:209], v[14:17]
	v_mfma_f32_16x16x32_bf16 v[10:13], v[182:185], v[206:209], v[10:13]
	v_mfma_f32_16x16x32_bf16 v[6:9], v[174:177], v[214:217], v[6:9]
	v_mfma_f32_16x16x32_bf16 v[2:5], v[182:185], v[214:217], v[2:5]
	v_mfma_f32_16x16x32_bf16 v[30:33], v[178:181], v[194:197], v[30:33]
	v_mfma_f32_16x16x32_bf16 v[26:29], v[186:189], v[194:197], v[26:29]
	v_mfma_f32_16x16x32_bf16 v[22:25], v[178:181], v[202:205], v[22:25]
	v_mfma_f32_16x16x32_bf16 v[18:21], v[186:189], v[202:205], v[18:21]
	v_mfma_f32_16x16x32_bf16 v[14:17], v[178:181], v[210:213], v[14:17]
	v_mfma_f32_16x16x32_bf16 v[10:13], v[186:189], v[210:213], v[10:13]
	v_mfma_f32_16x16x32_bf16 v[6:9], v[178:181], v[218:221], v[6:9]
	v_mfma_f32_16x16x32_bf16 v[2:5], v[186:189], v[218:221], v[2:5]
	s_barrier
; #define PG8_STAGE(bufoff, gbase, voff) do { _Pragma("unroll") for (int _i = 0; _i < 2; ++_i) \
;         __builtin_amdgcn_global_load_lds((const unsigned*)((const char*)(gbase) + (voff)[_i]), (LAS unsigned*)(lds + (bufoff) + ldsw + _i * 8192), 16, 0, 0); } while (0)
; #define PG8_LDA(dst, b, h) do { _Pragma("unroll") for (int m = 0; m < 4; ++m) _Pragma("unroll") for (int k = 0; k < 2; ++k) dst[m][k] = *(const LAS bf16x8*)(lds + PG8_SA(b, h) + aoff + m * 2048 + k * 1024); } while (0)
; #define PG8_LDB(dst, b, h) do { _Pragma("unroll") for (int n = 0; n < 2; ++n) _Pragma("unroll") for (int k = 0; k < 2; ++k) dst[n][k] = *(const LAS bf16x8*)(lds + PG8_SB(b, h) + boff + n * 2048 + k * 1024); } while (0)
; #define PG8_WAIT_V(n) asm volatile("s_waitcnt vmcnt(" #n ")" ::: "memory")
; #define PG8_WAIT_L(n) asm volatile("s_waitcnt lgkmcnt(" #n ")" ::: "memory")
; #define PG8_BAR __builtin_amdgcn_s_barrier()
; #define PG8_SCHED __builtin_amdgcn_sched_barrier(0)
; template <class Epi, class Sched, bool I8 = false>
; __device__ __forceinline__ void gemm_phase(LAS unsigned char* lds, const Gemm g, const Sched& S, const Epi& E) {
;     ...
;         for (int t = 0; t < nt; t += 2) {
;             const bool last = (t == nt - 2);
;     ...
;             PG8_LDB(B0, 1, 0); PG8_LDB(B1, 1, 1); PG8_SCHED; PG8_LDA(At, 1, 0); PG8_STAGE(PG8_SA(0, 1), a2 + hstepA, voffA);
;             PG8_WAIT_V(8); PG8_WAIT_L(0); PG8_BAR; PG8_MMA(0, 0, At, B0); PG8_MMA(0, 1, At, B1); PG8_BAR; PG8_SCHED;
;             PG8_LDA(At, 1, 1); PG8_STAGE(PG8_SB(1, 0), b3, voffB); PG8_STAGE(PG8_SB(1, 1), b3 + hstepB, voffB); PG8_STAGE(PG8_SA(1, 0), a3, voffA);
;             PG8_WAIT_V(8); PG8_WAIT_L(0); PG8_BAR; PG8_MMA(1, 0, At, B0); PG8_MMA(1, 1, At, B1); PG8_BAR; PG8_SCHED;
	s_setprio 1
	s_add_i32 s46, 0, 0x18000
	v_add_u32_e32 v155, s46, v165
	s_add_i32 s47, 0, 0x1c000
	ds_read_b128 v[130:133], v155
	ds_read_b128 v[134:137], v155 offset:1024
	ds_read_b128 v[158:161], v155 offset:2048
	ds_read_b128 v[170:173], v155 offset:3072
	v_add_u32_e32 v155, s47, v165
	ds_read_b128 v[174:177], v155
	ds_read_b128 v[178:181], v155 offset:1024
	ds_read_b128 v[182:185], v155 offset:2048
	ds_read_b128 v[186:189], v155 offset:3072
	s_mov_b32 m0, s26
	s_nop 0
	global_load_lds_dwordx4 v144, s[16:17]
	s_mov_b32 m0, s27
	s_nop 0
	global_load_lds_dwordx4 v140, s[16:17]
	s_add_u32 s16, s16, 0x4000
	s_addc_u32 s17, s17, 0
	s_mov_b32 m0, s28
	ds_read_b128 v[190:193], v168 offset:32768
	ds_read_b128 v[194:197], v168 offset:33792
	ds_read_b128 v[198:201], v168 offset:34816
	ds_read_b128 v[202:205], v168 offset:35840
	ds_read_b128 v[206:209], v168 offset:36864
	ds_read_b128 v[210:213], v168 offset:37888
	ds_read_b128 v[214:217], v168 offset:38912
	ds_read_b128 v[218:221], v168 offset:39936
	global_load_lds_dwordx4 v144, s[16:17]
	s_mov_b32 m0, s29
	s_nop 0
	global_load_lds_dwordx4 v140, s[16:17]
	s_setprio 0
	s_waitcnt vmcnt(8)
	s_waitcnt lgkmcnt(0)
	s_barrier
	s_waitcnt lgkmcnt(0)
	v_mfma_f32_16x16x32_bf16 v[126:129], v[130:133], v[190:193], v[126:129]
	v_mfma_f32_16x16x32_bf16 v[122:125], v[158:161], v[190:193], v[122:125]
	v_mfma_f32_16x16x32_bf16 v[118:121], v[130:133], v[198:201], v[118:121]
	v_mfma_f32_16x16x32_bf16 v[114:117], v[158:161], v[198:201], v[114:117]
	v_mfma_f32_16x16x32_bf16 v[110:113], v[130:133], v[206:209], v[110:113]
	v_mfma_f32_16x16x32_bf16 v[106:109], v[158:161], v[206:209], v[106:109]
	v_mfma_f32_16x16x32_bf16 v[102:105], v[130:133], v[214:217], v[102:105]
	v_mfma_f32_16x16x32_bf16 v[98:101], v[158:161], v[214:217], v[98:101]
	v_mfma_f32_16x16x32_bf16 v[126:129], v[134:137], v[194:197], v[126:129]
	v_mfma_f32_16x16x32_bf16 v[122:125], v[170:173], v[194:197], v[122:125]
	v_mfma_f32_16x16x32_bf16 v[118:121], v[134:137], v[202:205], v[118:121]
	v_mfma_f32_16x16x32_bf16 v[114:117], v[170:173], v[202:205], v[114:117]
	v_mfma_f32_16x16x32_bf16 v[110:113], v[134:137], v[210:213], v[110:113]
	v_mfma_f32_16x16x32_bf16 v[106:109], v[170:173], v[210:213], v[106:109]
	v_mfma_f32_16x16x32_bf16 v[102:105], v[134:137], v[218:221], v[102:105]
	v_mfma_f32_16x16x32_bf16 v[98:101], v[170:173], v[218:221], v[98:101]
	v_mfma_f32_16x16x32_bf16 v[62:65], v[174:177], v[190:193], v[62:65]
	v_mfma_f32_16x16x32_bf16 v[58:61], v[182:185], v[190:193], v[58:61]
	v_mfma_f32_16x16x32_bf16 v[54:57], v[174:177], v[198:201], v[54:57]
	v_mfma_f32_16x16x32_bf16 v[50:53], v[182:185], v[198:201], v[50:53]
	v_mfma_f32_16x16x32_bf16 v[46:49], v[174:177], v[206:209], v[46:49]
	v_mfma_f32_16x16x32_bf16 v[42:45], v[182:185], v[206:209], v[42:45]
	v_mfma_f32_16x16x32_bf16 v[38:41], v[174:177], v[214:217], v[38:41]
	v_mfma_f32_16x16x32_bf16 v[34:37], v[182:185], v[214:217], v[34:37]
	v_mfma_f32_16x16x32_bf16 v[62:65], v[178:181], v[194:197], v[62:65]
	v_mfma_f32_16x16x32_bf16 v[58:61], v[186:189], v[194:197], v[58:61]
	v_mfma_f32_16x16x32_bf16 v[54:57], v[178:181], v[202:205], v[54:57]
	v_mfma_f32_16x16x32_bf16 v[50:53], v[186:189], v[202:205], v[50:53]
	v_mfma_f32_16x16x32_bf16 v[46:49], v[178:181], v[210:213], v[46:49]
	v_mfma_f32_16x16x32_bf16 v[42:45], v[186:189], v[210:213], v[42:45]
	v_mfma_f32_16x16x32_bf16 v[38:41], v[178:181], v[218:221], v[38:41]
	v_mfma_f32_16x16x32_bf16 v[34:37], v[186:189], v[218:221], v[34:37]
	s_barrier
	s_setprio 1
	s_add_u32 s16, s14, 0x8000
	s_addc_u32 s17, s15, 0
	s_add_i32 s46, s46, s22
	s_mov_b32 m0, s46
	ds_read_b128 v[190:193], v168 offset:49152
	ds_read_b128 v[194:197], v168 offset:50176
	ds_read_b128 v[198:201], v168 offset:51200
	ds_read_b128 v[202:205], v168 offset:52224
	ds_read_b128 v[206:209], v168 offset:53248
	ds_read_b128 v[210:213], v168 offset:54272
	ds_read_b128 v[214:217], v168 offset:55296
	ds_read_b128 v[218:221], v168 offset:56320
	global_load_lds_dwordx4 v142, s[16:17]
	s_add_i32 m0, s46, 0x2000
	s_add_u32 s14, s14, 0xc000
	v_lshl_add_u64 v[162:163], s[16:17], 0, v[138:139]
	s_addc_u32 s15, s15, 0
	s_add_i32 s16, s47, s22
	global_load_lds_dwordx4 v[162:163], off
	s_mov_b32 m0, s16
	s_nop 0
	global_load_lds_dwordx4 v142, s[14:15]
	s_add_i32 m0, s16, 0x2000
	s_nop 0
	global_load_lds_dwordx4 v138, s[14:15]
	s_setprio 0
	s_waitcnt vmcnt(6)
	s_waitcnt lgkmcnt(0)
	s_barrier
	s_waitcnt lgkmcnt(0)
	v_mfma_f32_16x16x32_bf16 v[94:97], v[130:133], v[190:193], v[94:97]
	v_mfma_f32_16x16x32_bf16 v[90:93], v[158:161], v[190:193], v[90:93]
	v_mfma_f32_16x16x32_bf16 v[86:89], v[130:133], v[198:201], v[86:89]
	v_mfma_f32_16x16x32_bf16 v[82:85], v[158:161], v[198:201], v[82:85]
	v_mfma_f32_16x16x32_bf16 v[78:81], v[130:133], v[206:209], v[78:81]
	v_mfma_f32_16x16x32_bf16 v[74:77], v[158:161], v[206:209], v[74:77]
	v_mfma_f32_16x16x32_bf16 v[70:73], v[130:133], v[214:217], v[70:73]
	v_mfma_f32_16x16x32_bf16 v[66:69], v[158:161], v[214:217], v[66:69]
	v_mfma_f32_16x16x32_bf16 v[94:97], v[134:137], v[194:197], v[94:97]
	v_mfma_f32_16x16x32_bf16 v[90:93], v[170:173], v[194:197], v[90:93]
	v_mfma_f32_16x16x32_bf16 v[86:89], v[134:137], v[202:205], v[86:89]
	v_mfma_f32_16x16x32_bf16 v[82:85], v[170:173], v[202:205], v[82:85]
	v_mfma_f32_16x16x32_bf16 v[78:81], v[134:137], v[210:213], v[78:81]
	v_mfma_f32_16x16x32_bf16 v[74:77], v[170:173], v[210:213], v[74:77]
	v_mfma_f32_16x16x32_bf16 v[70:73], v[134:137], v[218:221], v[70:73]
	v_mfma_f32_16x16x32_bf16 v[66:69], v[170:173], v[218:221], v[66:69]
	v_mfma_f32_16x16x32_bf16 v[30:33], v[174:177], v[190:193], v[30:33]
	v_mfma_f32_16x16x32_bf16 v[26:29], v[182:185], v[190:193], v[26:29]
	v_mfma_f32_16x16x32_bf16 v[22:25], v[174:177], v[198:201], v[22:25]
	v_mfma_f32_16x16x32_bf16 v[18:21], v[182:185], v[198:201], v[18:21]
	v_mfma_f32_16x16x32_bf16 v[14:17], v[174:177], v[206:209], v[14:17]
	v_mfma_f32_16x16x32_bf16 v[10:13], v[182:185], v[206:209], v[10:13]
	v_mfma_f32_16x16x32_bf16 v[6:9], v[174:177], v[214:217], v[6:9]
	v_mfma_f32_16x16x32_bf16 v[2:5], v[182:185], v[214:217], v[2:5]
	v_mfma_f32_16x16x32_bf16 v[30:33], v[178:181], v[194:197], v[30:33]
	v_mfma_f32_16x16x32_bf16 v[26:29], v[186:189], v[194:197], v[26:29]
	v_mfma_f32_16x16x32_bf16 v[22:25], v[178:181], v[202:205], v[22:25]
	v_mfma_f32_16x16x32_bf16 v[18:21], v[186:189], v[202:205], v[18:21]
	v_mfma_f32_16x16x32_bf16 v[14:17], v[178:181], v[210:213], v[14:17]
	v_mfma_f32_16x16x32_bf16 v[10:13], v[186:189], v[210:213], v[10:13]
	v_mfma_f32_16x16x32_bf16 v[6:9], v[178:181], v[218:221], v[6:9]
	v_mfma_f32_16x16x32_bf16 v[2:5], v[186:189], v[218:221], v[2:5]
	s_barrier
	s_add_i32 s45, s45, 2
	s_add_u32 s10, s10, 0x10000
	s_addc_u32 s11, s11, 0
	s_add_u32 s43, s43, 0x10000
	s_addc_u32 s44, s44, 0
	s_cmp_gt_u32 s45, 5
	s_cbranch_scc0 .LBB0_2685
	s_and_b64 vcc, exec, s[6:7]
	s_cbranch_vccz .LBB0_2688
	s_barrier

; #define PG8_STAGE(bufoff, gbase, voff) do { _Pragma("unroll") for (int _i = 0; _i < 2; ++_i) \
;         __builtin_amdgcn_global_load_lds((const unsigned*)((const char*)(gbase) + (voff)[_i]), (LAS unsigned*)(lds + (bufoff) + ldsw + _i * 8192), 16, 0, 0); } while (0)
; #define PG8_LDA(dst, b, h) do { _Pragma("unroll") for (int m = 0; m < 4; ++m) _Pragma("unroll") for (int k = 0; k < 2; ++k) dst[m][k] = *(const LAS bf16x8*)(lds + PG8_SA(b, h) + aoff + m * 2048 + k * 1024); } while (0)
; #define PG8_LDB(dst, b, h) do { _Pragma("unroll") for (int n = 0; n < 2; ++n) _Pragma("unroll") for (int k = 0; k < 2; ++k) dst[n][k] = *(const LAS bf16x8*)(lds + PG8_SB(b, h) + boff + n * 2048 + k * 1024); } while (0)
; #define PG8_WAIT_V(n) asm volatile("s_waitcnt vmcnt(" #n ")" ::: "memory")
; #define PG8_WAIT_L(n) asm volatile("s_waitcnt lgkmcnt(" #n ")" ::: "memory")
; #define PG8_BAR __builtin_amdgcn_s_barrier()
; #define PG8_SCHED __builtin_amdgcn_sched_barrier(0)
; template <class Epi, class Sched, bool I8 = false>
; __device__ __forceinline__ void gemm_phase(LAS unsigned char* lds, const Gemm g, const Sched& S, const Epi& E) {
;     ...
;             PG8_LDB(B0, 0, 0); PG8_LDB(B1, 0, 1); PG8_SCHED; PG8_LDA(At, 0, 0); PG8_STAGE(PG8_SA(1, 1), a1 + hstepA, voffA);
;             PG8_WAIT_V(8); PG8_WAIT_L(0); PG8_BAR; PG8_MMA(0, 0, At, B0); PG8_MMA(0, 1, At, B1); PG8_BAR; PG8_SCHED;
;             PG8_LDA(At, 0, 1); PG8_STAGE(PG8_SB(0, 0), b2, voffB); PG8_STAGE(PG8_SB(0, 1), b2 + hstepB, voffB); PG8_STAGE(PG8_SA(0, 0), a2, voffA);
;             PG8_WAIT_V(8); PG8_WAIT_L(0); PG8_BAR; PG8_MMA(1, 0, At, B0); PG8_MMA(1, 1, At, B1); PG8_BAR; PG8_SCHED;
.LBB0_3744:
	s_setprio 1
	ds_read_b128 v[130:133], v231
	ds_read_b128 v[134:137], v231 offset:1024
	ds_read_b128 v[138:141], v231 offset:2048
	ds_read_b128 v[142:145], v231 offset:3072
	ds_read_b128 v[146:149], v232
	ds_read_b128 v[150:153], v232 offset:1024
	ds_read_b128 v[154:157], v232 offset:2048
	ds_read_b128 v[158:161], v232 offset:3072
	s_add_u32 s34, s30, 0x4000
	s_addc_u32 s35, s31, 0
	s_cmp_eq_u32 s59, 60
	s_cselect_b32 s38, s23, s34
	s_cselect_b32 s39, s5, s35
	s_cselect_b32 s36, s29, s57
	s_cselect_b32 s37, s21, s58
	s_add_u32 s34, s38, 0x8000
	s_addc_u32 s35, s39, 0
	s_sub_u32 s98, s30, 0x4000
	s_subb_u32 s99, s31, 0
	s_mov_b32 m0, s51
	s_nop 0
	global_load_lds_dwordx4 v194, s[98:99]
	s_mov_b32 m0, s52
	s_nop 0
	global_load_lds_dwordx4 v198, s[98:99]
	s_add_i32 m0, s44, 0xc000
	ds_read_b128 v[162:165], v233
	ds_read_b128 v[166:169], v233 offset:1024
	ds_read_b128 v[170:173], v233 offset:2048
	ds_read_b128 v[174:177], v233 offset:3072
	ds_read_b128 v[178:181], v233 offset:4096
	ds_read_b128 v[182:185], v233 offset:5120
	ds_read_b128 v[186:189], v233 offset:6144
	ds_read_b128 v[190:193], v233 offset:7168
	global_load_lds_dwordx4 v204, s[30:31]
	s_add_i32 m0, s44, 0xe000
	s_nop 0
	global_load_lds_dwordx4 v206, s[30:31]
	s_setprio 0
	s_waitcnt vmcnt(8)
	s_waitcnt lgkmcnt(0)
	s_barrier
	s_waitcnt lgkmcnt(0)
	v_mfma_f32_16x16x32_bf16 v[126:129], v[130:133], v[162:165], v[126:129]
	v_mfma_f32_16x16x32_bf16 v[122:125], v[138:141], v[162:165], v[122:125]
	v_mfma_f32_16x16x32_bf16 v[118:121], v[130:133], v[170:173], v[118:121]
	v_mfma_f32_16x16x32_bf16 v[110:113], v[138:141], v[170:173], v[110:113]
	v_mfma_f32_16x16x32_bf16 v[102:105], v[130:133], v[178:181], v[102:105]
	v_mfma_f32_16x16x32_bf16 v[94:97], v[138:141], v[178:181], v[94:97]
	v_mfma_f32_16x16x32_bf16 v[86:89], v[130:133], v[186:189], v[86:89]
	v_mfma_f32_16x16x32_bf16 v[78:81], v[138:141], v[186:189], v[78:81]
	v_mfma_f32_16x16x32_bf16 v[126:129], v[134:137], v[166:169], v[126:129]
	v_mfma_f32_16x16x32_bf16 v[122:125], v[142:145], v[166:169], v[122:125]
	v_mfma_f32_16x16x32_bf16 v[118:121], v[134:137], v[174:177], v[118:121]
	v_mfma_f32_16x16x32_bf16 v[110:113], v[142:145], v[174:177], v[110:113]
	v_mfma_f32_16x16x32_bf16 v[102:105], v[134:137], v[182:185], v[102:105]
	v_mfma_f32_16x16x32_bf16 v[94:97], v[142:145], v[182:185], v[94:97]
	v_mfma_f32_16x16x32_bf16 v[86:89], v[134:137], v[190:193], v[86:89]
	v_mfma_f32_16x16x32_bf16 v[78:81], v[142:145], v[190:193], v[78:81]
	v_mfma_f32_16x16x32_bf16 v[114:117], v[146:149], v[162:165], v[114:117]
	v_mfma_f32_16x16x32_bf16 v[106:109], v[154:157], v[162:165], v[106:109]
	v_mfma_f32_16x16x32_bf16 v[98:101], v[146:149], v[170:173], v[98:101]
	v_mfma_f32_16x16x32_bf16 v[90:93], v[154:157], v[170:173], v[90:93]
	v_mfma_f32_16x16x32_bf16 v[82:85], v[146:149], v[178:181], v[82:85]
	v_mfma_f32_16x16x32_bf16 v[74:77], v[154:157], v[178:181], v[74:77]
	v_mfma_f32_16x16x32_bf16 v[70:73], v[146:149], v[186:189], v[70:73]
	v_mfma_f32_16x16x32_bf16 v[66:69], v[154:157], v[186:189], v[66:69]
	v_mfma_f32_16x16x32_bf16 v[114:117], v[150:153], v[166:169], v[114:117]
	v_mfma_f32_16x16x32_bf16 v[106:109], v[158:161], v[166:169], v[106:109]
	v_mfma_f32_16x16x32_bf16 v[98:101], v[150:153], v[174:177], v[98:101]
	v_mfma_f32_16x16x32_bf16 v[90:93], v[158:161], v[174:177], v[90:93]
	v_mfma_f32_16x16x32_bf16 v[82:85], v[150:153], v[182:185], v[82:85]
	v_mfma_f32_16x16x32_bf16 v[74:77], v[158:161], v[182:185], v[74:77]
	v_mfma_f32_16x16x32_bf16 v[70:73], v[150:153], v[190:193], v[70:73]
	v_mfma_f32_16x16x32_bf16 v[66:69], v[158:161], v[190:193], v[66:69]
	s_barrier
	s_setprio 1
	s_add_i32 s60, s55, s43
	s_mov_b32 m0, s60
	ds_read_b128 v[162:165], v233 offset:16384
	ds_read_b128 v[166:169], v233 offset:17408
	ds_read_b128 v[170:173], v233 offset:18432
	ds_read_b128 v[174:177], v233 offset:19456
	ds_read_b128 v[178:181], v233 offset:20480
	ds_read_b128 v[182:185], v233 offset:21504
	ds_read_b128 v[186:189], v233 offset:22528
	ds_read_b128 v[190:193], v233 offset:23552
	global_load_lds_dwordx4 v196, s[36:37]
	s_add_i32 m0, s60, 0x2000
	s_add_u32 s60, s36, 0x4000
	s_addc_u32 s61, s37, 0
	s_add_i32 s62, s56, s43
	global_load_lds_dwordx4 v200, s[36:37]
	s_mov_b32 m0, s62
	s_nop 0
	global_load_lds_dwordx4 v196, s[60:61]
	s_add_i32 m0, s62, 0x2000
	s_nop 0
	global_load_lds_dwordx4 v200, s[60:61]
	s_setprio 0
	s_waitcnt vmcnt(6)
	s_waitcnt lgkmcnt(0)
	s_barrier
	s_waitcnt lgkmcnt(0)
	v_mfma_f32_16x16x32_bf16 v[62:65], v[130:133], v[162:165], v[62:65]
	v_mfma_f32_16x16x32_bf16 v[58:61], v[138:141], v[162:165], v[58:61]
	v_mfma_f32_16x16x32_bf16 v[54:57], v[130:133], v[170:173], v[54:57]
	v_mfma_f32_16x16x32_bf16 v[46:49], v[138:141], v[170:173], v[46:49]
	v_mfma_f32_16x16x32_bf16 v[38:41], v[130:133], v[178:181], v[38:41]
	v_mfma_f32_16x16x32_bf16 v[30:33], v[138:141], v[178:181], v[30:33]
	v_mfma_f32_16x16x32_bf16 v[22:25], v[130:133], v[186:189], v[22:25]
	v_mfma_f32_16x16x32_bf16 v[14:17], v[138:141], v[186:189], v[14:17]
	v_mfma_f32_16x16x32_bf16 v[62:65], v[134:137], v[166:169], v[62:65]
	v_mfma_f32_16x16x32_bf16 v[58:61], v[142:145], v[166:169], v[58:61]
	v_mfma_f32_16x16x32_bf16 v[54:57], v[134:137], v[174:177], v[54:57]
	v_mfma_f32_16x16x32_bf16 v[46:49], v[142:145], v[174:177], v[46:49]
	v_mfma_f32_16x16x32_bf16 v[38:41], v[134:137], v[182:185], v[38:41]
	v_mfma_f32_16x16x32_bf16 v[30:33], v[142:145], v[182:185], v[30:33]
	v_mfma_f32_16x16x32_bf16 v[22:25], v[134:137], v[190:193], v[22:25]
	v_mfma_f32_16x16x32_bf16 v[14:17], v[142:145], v[190:193], v[14:17]
	v_mfma_f32_16x16x32_bf16 v[50:53], v[146:149], v[162:165], v[50:53]
	v_mfma_f32_16x16x32_bf16 v[42:45], v[154:157], v[162:165], v[42:45]
	v_mfma_f32_16x16x32_bf16 v[34:37], v[146:149], v[170:173], v[34:37]
	v_mfma_f32_16x16x32_bf16 v[26:29], v[154:157], v[170:173], v[26:29]
	v_mfma_f32_16x16x32_bf16 v[18:21], v[146:149], v[178:181], v[18:21]
	v_mfma_f32_16x16x32_bf16 v[10:13], v[154:157], v[178:181], v[10:13]
	v_mfma_f32_16x16x32_bf16 v[6:9], v[146:149], v[186:189], v[6:9]
	v_mfma_f32_16x16x32_bf16 v[2:5], v[154:157], v[186:189], v[2:5]
	v_mfma_f32_16x16x32_bf16 v[50:53], v[150:153], v[166:169], v[50:53]
	v_mfma_f32_16x16x32_bf16 v[42:45], v[158:161], v[166:169], v[42:45]
	v_mfma_f32_16x16x32_bf16 v[34:37], v[150:153], v[174:177], v[34:37]
	v_mfma_f32_16x16x32_bf16 v[26:29], v[158:161], v[174:177], v[26:29]
	v_mfma_f32_16x16x32_bf16 v[18:21], v[150:153], v[182:185], v[18:21]
	v_mfma_f32_16x16x32_bf16 v[10:13], v[158:161], v[182:185], v[10:13]
	v_mfma_f32_16x16x32_bf16 v[6:9], v[150:153], v[190:193], v[6:9]
	v_mfma_f32_16x16x32_bf16 v[2:5], v[158:161], v[190:193], v[2:5]
	s_barrier
; #define PG8_STAGE(bufoff, gbase, voff) do { _Pragma("unroll") for (int _i = 0; _i < 2; ++_i) \
;         __builtin_amdgcn_global_load_lds((const unsigned*)((const char*)(gbase) + (voff)[_i]), (LAS unsigned*)(lds + (bufoff) + ldsw + _i * 8192), 16, 0, 0); } while (0)
; #define PG8_LDA(dst, b, h) do { _Pragma("unroll") for (int m = 0; m < 4; ++m) _Pragma("unroll") for (int k = 0; k < 2; ++k) dst[m][k] = *(const LAS bf16x8*)(lds + PG8_SA(b, h) + aoff + m * 2048 + k * 1024); } while (0)
; #define PG8_LDB(dst, b, h) do { _Pragma("unroll") for (int n = 0; n < 2; ++n) _Pragma("unroll") for (int k = 0; k < 2; ++k) dst[n][k] = *(const LAS bf16x8*)(lds + PG8_SB(b, h) + boff + n * 2048 + k * 1024); } while (0)
; #define PG8_WAIT_V(n) asm volatile("s_waitcnt vmcnt(" #n ")" ::: "memory")
; template <class Epi, class Sched, bool I8 = false>
; __device__ __forceinline__ void gemm_phase(LAS unsigned char* lds, const Gemm g, const Sched& S, const Epi& E) {
;     ...
;         for (int t = 0; t < nt; t += 2) {
;             const bool last = (t == nt - 2);
;             const char* a1 = cA + (size_t)(t + 1) * kstep;
;             const char* a2 = last ? nA : cA + (size_t)(t + 2) * kstep; const char* b2 = last ? nB : cB + (size_t)(t + 2) * kstep;
;             const char* a3 = a2 + kstep; const char* b3 = b2 + kstep;
;             PG8_LDB(B0, 0, 0); PG8_LDB(B1, 0, 1); PG8_SCHED; PG8_LDA(At, 0, 0); PG8_STAGE(PG8_SA(1, 1), a1 + hstepA, voffA);
;             PG8_WAIT_V(8); PG8_WAIT_L(0); PG8_BAR; PG8_MMA(0, 0, At, B0); PG8_MMA(0, 1, At, B1); PG8_BAR; PG8_SCHED;
;             PG8_LDA(At, 0, 1); PG8_STAGE(PG8_SB(0, 0), b2, voffB); PG8_STAGE(PG8_SB(0, 1), b2 + hstepB, voffB); PG8_STAGE(PG8_SA(0, 0), a2, voffA);
;             PG8_WAIT_V(8); PG8_WAIT_L(0); PG8_BAR; PG8_MMA(1, 0, At, B0); PG8_MMA(1, 1, At, B1); PG8_BAR; PG8_SCHED;
;             PG8_LDB(B0, 1, 0); PG8_LDB(B1, 1, 1); PG8_SCHED; PG8_LDA(At, 1, 0); PG8_STAGE(PG8_SA(0, 1), a2 + hstepA, voffA);
;             PG8_WAIT_V(8); PG8_WAIT_L(0); PG8_BAR; PG8_MMA(0, 0, At, B0); PG8_MMA(0, 1, At, B1); PG8_BAR; PG8_SCHED;
;             PG8_LDA(At, 1, 1); PG8_STAGE(PG8_SB(1, 0), b3, voffB); PG8_STAGE(PG8_SB(1, 1), b3 + hstepB, voffB); PG8_STAGE(PG8_SA(1, 0), a3, voffA);
;             PG8_WAIT_V(8); PG8_WAIT_L(0); PG8_BAR; PG8_MMA(1, 0, At, B0); PG8_MMA(1, 1, At, B1); PG8_BAR; PG8_SCHED;
;         }
;         if (wr == 0) PG8_BAR;
	s_setprio 1
	s_add_i32 s60, 0, 0x18000
	s_add_i32 s61, 0, 0x1c000
	v_add_u32_e32 v142, s60, v230
	v_add_u32_e32 v158, s61, v230
	ds_read_b128 v[130:133], v142
	ds_read_b128 v[134:137], v142 offset:1024
	ds_read_b128 v[138:141], v142 offset:2048
	ds_read_b128 v[142:145], v142 offset:3072
	ds_read_b128 v[146:149], v158
	ds_read_b128 v[150:153], v158 offset:1024
	ds_read_b128 v[154:157], v158 offset:2048
	ds_read_b128 v[158:161], v158 offset:3072
	s_mov_b32 m0, s44
	s_nop 0
	global_load_lds_dwordx4 v194, s[38:39]
	s_mov_b32 m0, s45
	s_nop 0
	global_load_lds_dwordx4 v198, s[38:39]
	s_add_u32 s38, s38, 0x4000
	s_addc_u32 s39, s39, 0
	s_mov_b32 m0, s46
	ds_read_b128 v[162:165], v233 offset:32768
	ds_read_b128 v[166:169], v233 offset:33792
	ds_read_b128 v[170:173], v233 offset:34816
	ds_read_b128 v[174:177], v233 offset:35840
	ds_read_b128 v[178:181], v233 offset:36864
	ds_read_b128 v[182:185], v233 offset:37888
	ds_read_b128 v[186:189], v233 offset:38912
	ds_read_b128 v[190:193], v233 offset:39936
	global_load_lds_dwordx4 v194, s[38:39]
	s_mov_b32 m0, s47
	s_nop 0
	global_load_lds_dwordx4 v198, s[38:39]
	s_setprio 0
	s_waitcnt vmcnt(8)
	s_waitcnt lgkmcnt(0)
	s_barrier
	s_waitcnt lgkmcnt(0)
	v_mfma_f32_16x16x32_bf16 v[126:129], v[130:133], v[162:165], v[126:129]
	v_mfma_f32_16x16x32_bf16 v[122:125], v[138:141], v[162:165], v[122:125]
	v_mfma_f32_16x16x32_bf16 v[118:121], v[130:133], v[170:173], v[118:121]
	v_mfma_f32_16x16x32_bf16 v[110:113], v[138:141], v[170:173], v[110:113]
	v_mfma_f32_16x16x32_bf16 v[102:105], v[130:133], v[178:181], v[102:105]
	v_mfma_f32_16x16x32_bf16 v[94:97], v[138:141], v[178:181], v[94:97]
	v_mfma_f32_16x16x32_bf16 v[86:89], v[130:133], v[186:189], v[86:89]
	v_mfma_f32_16x16x32_bf16 v[78:81], v[138:141], v[186:189], v[78:81]
	v_mfma_f32_16x16x32_bf16 v[126:129], v[134:137], v[166:169], v[126:129]
	v_mfma_f32_16x16x32_bf16 v[122:125], v[142:145], v[166:169], v[122:125]
	v_mfma_f32_16x16x32_bf16 v[118:121], v[134:137], v[174:177], v[118:121]
	v_mfma_f32_16x16x32_bf16 v[110:113], v[142:145], v[174:177], v[110:113]
	v_mfma_f32_16x16x32_bf16 v[102:105], v[134:137], v[182:185], v[102:105]
	v_mfma_f32_16x16x32_bf16 v[94:97], v[142:145], v[182:185], v[94:97]
	v_mfma_f32_16x16x32_bf16 v[86:89], v[134:137], v[190:193], v[86:89]
	v_mfma_f32_16x16x32_bf16 v[78:81], v[142:145], v[190:193], v[78:81]
	v_mfma_f32_16x16x32_bf16 v[114:117], v[146:149], v[162:165], v[114:117]
	v_mfma_f32_16x16x32_bf16 v[106:109], v[154:157], v[162:165], v[106:109]
	v_mfma_f32_16x16x32_bf16 v[98:101], v[146:149], v[170:173], v[98:101]
	v_mfma_f32_16x16x32_bf16 v[90:93], v[154:157], v[170:173], v[90:93]
	v_mfma_f32_16x16x32_bf16 v[82:85], v[146:149], v[178:181], v[82:85]
	v_mfma_f32_16x16x32_bf16 v[74:77], v[154:157], v[178:181], v[74:77]
	v_mfma_f32_16x16x32_bf16 v[70:73], v[146:149], v[186:189], v[70:73]
	v_mfma_f32_16x16x32_bf16 v[66:69], v[154:157], v[186:189], v[66:69]
	v_mfma_f32_16x16x32_bf16 v[114:117], v[150:153], v[166:169], v[114:117]
	v_mfma_f32_16x16x32_bf16 v[106:109], v[158:161], v[166:169], v[106:109]
	v_mfma_f32_16x16x32_bf16 v[98:101], v[150:153], v[174:177], v[98:101]
	v_mfma_f32_16x16x32_bf16 v[90:93], v[158:161], v[174:177], v[90:93]
	v_mfma_f32_16x16x32_bf16 v[82:85], v[150:153], v[182:185], v[82:85]
	v_mfma_f32_16x16x32_bf16 v[74:77], v[158:161], v[182:185], v[74:77]
	v_mfma_f32_16x16x32_bf16 v[70:73], v[150:153], v[190:193], v[70:73]
	v_mfma_f32_16x16x32_bf16 v[66:69], v[158:161], v[190:193], v[66:69]
	s_barrier
	s_setprio 1
	s_add_u32 s38, s36, 0x8000
	s_addc_u32 s39, s37, 0
	s_add_i32 s60, s60, s43
	s_mov_b32 m0, s60
	ds_read_b128 v[162:165], v233 offset:49152
	ds_read_b128 v[166:169], v233 offset:50176
	ds_read_b128 v[170:173], v233 offset:51200
	ds_read_b128 v[174:177], v233 offset:52224
	ds_read_b128 v[178:181], v233 offset:53248
	ds_read_b128 v[182:185], v233 offset:54272
	ds_read_b128 v[186:189], v233 offset:55296
	ds_read_b128 v[190:193], v233 offset:56320
	global_load_lds_dwordx4 v196, s[38:39]
	s_add_i32 m0, s60, 0x2000
	s_add_u32 s36, s36, 0xc000
	v_lshl_add_u64 v[212:213], s[38:39], 0, v[200:201]
	s_addc_u32 s37, s37, 0
	s_add_i32 s38, s61, s43
	global_load_lds_dwordx4 v[212:213], off
	s_mov_b32 m0, s38
	s_nop 0
	global_load_lds_dwordx4 v196, s[36:37]
	s_add_i32 m0, s38, 0x2000
	s_nop 0
	global_load_lds_dwordx4 v200, s[36:37]
	s_setprio 0
	s_waitcnt vmcnt(6)
	s_waitcnt lgkmcnt(0)
	s_barrier
	s_waitcnt lgkmcnt(0)
	v_mfma_f32_16x16x32_bf16 v[62:65], v[130:133], v[162:165], v[62:65]
	v_mfma_f32_16x16x32_bf16 v[58:61], v[138:141], v[162:165], v[58:61]
	v_mfma_f32_16x16x32_bf16 v[54:57], v[130:133], v[170:173], v[54:57]
	v_mfma_f32_16x16x32_bf16 v[46:49], v[138:141], v[170:173], v[46:49]
	v_mfma_f32_16x16x32_bf16 v[38:41], v[130:133], v[178:181], v[38:41]
	v_mfma_f32_16x16x32_bf16 v[30:33], v[138:141], v[178:181], v[30:33]
	v_mfma_f32_16x16x32_bf16 v[22:25], v[130:133], v[186:189], v[22:25]
	v_mfma_f32_16x16x32_bf16 v[14:17], v[138:141], v[186:189], v[14:17]
	v_mfma_f32_16x16x32_bf16 v[62:65], v[134:137], v[166:169], v[62:65]
	v_mfma_f32_16x16x32_bf16 v[58:61], v[142:145], v[166:169], v[58:61]
	v_mfma_f32_16x16x32_bf16 v[54:57], v[134:137], v[174:177], v[54:57]
	v_mfma_f32_16x16x32_bf16 v[46:49], v[142:145], v[174:177], v[46:49]
	v_mfma_f32_16x16x32_bf16 v[38:41], v[134:137], v[182:185], v[38:41]
	v_mfma_f32_16x16x32_bf16 v[30:33], v[142:145], v[182:185], v[30:33]
	v_mfma_f32_16x16x32_bf16 v[22:25], v[134:137], v[190:193], v[22:25]
	v_mfma_f32_16x16x32_bf16 v[14:17], v[142:145], v[190:193], v[14:17]
	v_mfma_f32_16x16x32_bf16 v[50:53], v[146:149], v[162:165], v[50:53]
	v_mfma_f32_16x16x32_bf16 v[42:45], v[154:157], v[162:165], v[42:45]
	v_mfma_f32_16x16x32_bf16 v[34:37], v[146:149], v[170:173], v[34:37]
	v_mfma_f32_16x16x32_bf16 v[26:29], v[154:157], v[170:173], v[26:29]
	v_mfma_f32_16x16x32_bf16 v[18:21], v[146:149], v[178:181], v[18:21]
	v_mfma_f32_16x16x32_bf16 v[10:13], v[154:157], v[178:181], v[10:13]
	v_mfma_f32_16x16x32_bf16 v[6:9], v[146:149], v[186:189], v[6:9]
	v_mfma_f32_16x16x32_bf16 v[2:5], v[154:157], v[186:189], v[2:5]
	v_mfma_f32_16x16x32_bf16 v[50:53], v[150:153], v[166:169], v[50:53]
	v_mfma_f32_16x16x32_bf16 v[42:45], v[158:161], v[166:169], v[42:45]
	v_mfma_f32_16x16x32_bf16 v[34:37], v[150:153], v[174:177], v[34:37]
	v_mfma_f32_16x16x32_bf16 v[26:29], v[158:161], v[174:177], v[26:29]
	v_mfma_f32_16x16x32_bf16 v[18:21], v[150:153], v[182:185], v[18:21]
	v_mfma_f32_16x16x32_bf16 v[10:13], v[158:161], v[182:185], v[10:13]
	v_mfma_f32_16x16x32_bf16 v[6:9], v[150:153], v[190:193], v[6:9]
	v_mfma_f32_16x16x32_bf16 v[2:5], v[158:161], v[190:193], v[2:5]
	s_barrier
	s_add_i32 s59, s59, 2
	s_add_u32 s30, s30, 0x10000
	s_addc_u32 s31, s31, 0
	s_add_u32 s57, s57, 0x10000
	s_addc_u32 s58, s58, 0
	s_cmp_gt_u32 s59, 61
	s_cbranch_scc0 .LBB0_3744
	s_and_b64 vcc, exec, s[6:7]
	s_cbranch_vccz .LBB0_3747
	s_barrier

; #define PG8_STAGE(bufoff, gbase, voff) do { _Pragma("unroll") for (int _i = 0; _i < 2; ++_i) \
;         __builtin_amdgcn_global_load_lds((const unsigned*)((const char*)(gbase) + (voff)[_i]), (LAS unsigned*)(lds + (bufoff) + ldsw + _i * 8192), 16, 0, 0); } while (0)
; #define PG8_LDA(dst, b, h) do { _Pragma("unroll") for (int m = 0; m < 4; ++m) _Pragma("unroll") for (int k = 0; k < 2; ++k) dst[m][k] = *(const LAS bf16x8*)(lds + PG8_SA(b, h) + aoff + m * 2048 + k * 1024); } while (0)
; #define PG8_LDB(dst, b, h) do { _Pragma("unroll") for (int n = 0; n < 2; ++n) _Pragma("unroll") for (int k = 0; k < 2; ++k) dst[n][k] = *(const LAS bf16x8*)(lds + PG8_SB(b, h) + boff + n * 2048 + k * 1024); } while (0)
; #define PG8_WAIT_V(n) asm volatile("s_waitcnt vmcnt(" #n ")" ::: "memory")
; #define PG8_WAIT_L(n) asm volatile("s_waitcnt lgkmcnt(" #n ")" ::: "memory")
; #define PG8_BAR __builtin_amdgcn_s_barrier()
; #define PG8_SCHED __builtin_amdgcn_sched_barrier(0)
; template <class Epi, class Sched, bool I8 = false>
; __device__ __forceinline__ void gemm_phase(LAS unsigned char* lds, const Gemm g, const Sched& S, const Epi& E) {
;     ...
;             const bool last = (t == nt - 2);
;             const char* a1 = cA + (size_t)(t + 1) * kstep;
;             const char* a2 = last ? nA : cA + (size_t)(t + 2) * kstep; const char* b2 = last ? nB : cB + (size_t)(t + 2) * kstep;
;             const char* a3 = a2 + kstep; const char* b3 = b2 + kstep;
;             PG8_LDB(B0, 0, 0); PG8_LDB(B1, 0, 1); PG8_SCHED; PG8_LDA(At, 0, 0); PG8_STAGE(PG8_SA(1, 1), a1 + hstepA, voffA);
;             PG8_WAIT_V(8); PG8_WAIT_L(0); PG8_BAR; PG8_MMA(0, 0, At, B0); PG8_MMA(0, 1, At, B1); PG8_BAR; PG8_SCHED;
;             PG8_LDA(At, 0, 1); PG8_STAGE(PG8_SB(0, 0), b2, voffB); PG8_STAGE(PG8_SB(0, 1), b2 + hstepB, voffB); PG8_STAGE(PG8_SA(0, 0), a2, voffA);
;             PG8_WAIT_V(8); PG8_WAIT_L(0); PG8_BAR; PG8_MMA(1, 0, At, B0); PG8_MMA(1, 1, At, B1); PG8_BAR; PG8_SCHED;
.LBB0_4168:
	s_setprio 1
	ds_read_b128 v[66:69], v178
	ds_read_b128 v[70:73], v178 offset:1024
	ds_read_b128 v[74:77], v178 offset:2048
	ds_read_b128 v[78:81], v178 offset:3072
	ds_read_b128 v[146:149], v179
	ds_read_b128 v[150:153], v179 offset:1024
	ds_read_b128 v[172:175], v179 offset:2048
	ds_read_b128 v[182:185], v179 offset:3072
	s_add_u32 s22, s20, 0x4000
	s_addc_u32 s23, s21, 0
	s_cmpk_eq_i32 s51, 0x52
	s_cselect_b32 s26, s0, s22
	s_cselect_b32 s27, s1, s23
	s_cselect_b32 s24, s18, s49
	s_cselect_b32 s25, s19, s50
	s_add_u32 s22, s26, 0x8000
	s_addc_u32 s23, s27, 0
	s_sub_u32 s98, s20, 0x4000
	s_subb_u32 s99, s21, 0
	s_mov_b32 m0, s39
	s_nop 0
	global_load_lds_dwordx4 v154, s[98:99]
	s_mov_b32 m0, s40
	s_nop 0
	global_load_lds_dwordx4 v158, s[98:99]
	s_add_i32 m0, s34, 0xc000
	ds_read_b128 v[186:189], v180
	ds_read_b128 v[190:193], v180 offset:1024
	ds_read_b128 v[194:197], v180 offset:2048
	ds_read_b128 v[198:201], v180 offset:3072
	ds_read_b128 v[202:205], v180 offset:4096
	ds_read_b128 v[206:209], v180 offset:5120
	ds_read_b128 v[210:213], v180 offset:6144
	ds_read_b128 v[214:217], v180 offset:7168
	global_load_lds_dwordx4 v164, s[20:21]
	s_add_i32 m0, s34, 0xe000
	s_nop 0
	global_load_lds_dwordx4 v166, s[20:21]
	s_setprio 0
	s_waitcnt vmcnt(8)
	s_waitcnt lgkmcnt(0)
	s_barrier
	s_waitcnt lgkmcnt(0)
	v_mfma_i32_16x16x64_i8 v[142:145], v[66:69], v[186:189], v[142:145]
	v_mfma_i32_16x16x64_i8 v[138:141], v[74:77], v[186:189], v[138:141]
	v_mfma_i32_16x16x64_i8 v[126:129], v[66:69], v[194:197], v[126:129]
	v_mfma_i32_16x16x64_i8 v[122:125], v[74:77], v[194:197], v[122:125]
	v_mfma_i32_16x16x64_i8 v[110:113], v[66:69], v[202:205], v[110:113]
	v_mfma_i32_16x16x64_i8 v[106:109], v[74:77], v[202:205], v[106:109]
	v_mfma_i32_16x16x64_i8 v[94:97], v[66:69], v[210:213], v[94:97]
	v_mfma_i32_16x16x64_i8 v[90:93], v[74:77], v[210:213], v[90:93]
	v_mfma_i32_16x16x64_i8 v[142:145], v[70:73], v[190:193], v[142:145]
	v_mfma_i32_16x16x64_i8 v[138:141], v[78:81], v[190:193], v[138:141]
	v_mfma_i32_16x16x64_i8 v[126:129], v[70:73], v[198:201], v[126:129]
	v_mfma_i32_16x16x64_i8 v[122:125], v[78:81], v[198:201], v[122:125]
	v_mfma_i32_16x16x64_i8 v[110:113], v[70:73], v[206:209], v[110:113]
	v_mfma_i32_16x16x64_i8 v[106:109], v[78:81], v[206:209], v[106:109]
	v_mfma_i32_16x16x64_i8 v[94:97], v[70:73], v[214:217], v[94:97]
	v_mfma_i32_16x16x64_i8 v[90:93], v[78:81], v[214:217], v[90:93]
	v_mfma_i32_16x16x64_i8 v[134:137], v[146:149], v[186:189], v[134:137]
	v_mfma_i32_16x16x64_i8 v[130:133], v[172:175], v[186:189], v[130:133]
	v_mfma_i32_16x16x64_i8 v[118:121], v[146:149], v[194:197], v[118:121]
	v_mfma_i32_16x16x64_i8 v[114:117], v[172:175], v[194:197], v[114:117]
	v_mfma_i32_16x16x64_i8 v[102:105], v[146:149], v[202:205], v[102:105]
	v_mfma_i32_16x16x64_i8 v[98:101], v[172:175], v[202:205], v[98:101]
	v_mfma_i32_16x16x64_i8 v[86:89], v[146:149], v[210:213], v[86:89]
	v_mfma_i32_16x16x64_i8 v[82:85], v[172:175], v[210:213], v[82:85]
	v_mfma_i32_16x16x64_i8 v[134:137], v[150:153], v[190:193], v[134:137]
	v_mfma_i32_16x16x64_i8 v[130:133], v[182:185], v[190:193], v[130:133]
	v_mfma_i32_16x16x64_i8 v[118:121], v[150:153], v[198:201], v[118:121]
	v_mfma_i32_16x16x64_i8 v[114:117], v[182:185], v[198:201], v[114:117]
	v_mfma_i32_16x16x64_i8 v[102:105], v[150:153], v[206:209], v[102:105]
	v_mfma_i32_16x16x64_i8 v[98:101], v[182:185], v[206:209], v[98:101]
	v_mfma_i32_16x16x64_i8 v[86:89], v[150:153], v[214:217], v[86:89]
	v_mfma_i32_16x16x64_i8 v[82:85], v[182:185], v[214:217], v[82:85]
	s_barrier
	s_setprio 1
	s_add_i32 s52, s43, s33
	s_mov_b32 m0, s52
	ds_read_b128 v[186:189], v180 offset:16384
	ds_read_b128 v[190:193], v180 offset:17408
	ds_read_b128 v[194:197], v180 offset:18432
	ds_read_b128 v[198:201], v180 offset:19456
	ds_read_b128 v[202:205], v180 offset:20480
	ds_read_b128 v[206:209], v180 offset:21504
	ds_read_b128 v[210:213], v180 offset:22528
	ds_read_b128 v[214:217], v180 offset:23552
	global_load_lds_dwordx4 v156, s[24:25]
	s_add_i32 m0, s52, 0x2000
	s_add_u32 s52, s24, 0x4000
	s_addc_u32 s53, s25, 0
	s_add_i32 s54, s44, s33
	global_load_lds_dwordx4 v160, s[24:25]
	s_mov_b32 m0, s54
	s_nop 0
	global_load_lds_dwordx4 v156, s[52:53]
	s_add_i32 m0, s54, 0x2000
	s_nop 0
	global_load_lds_dwordx4 v160, s[52:53]
	s_setprio 0
	s_waitcnt vmcnt(6)
	s_waitcnt lgkmcnt(0)
	s_barrier
	s_waitcnt lgkmcnt(0)
	v_mfma_i32_16x16x64_i8 v[62:65], v[66:69], v[186:189], v[62:65]
	v_mfma_i32_16x16x64_i8 v[58:61], v[74:77], v[186:189], v[58:61]
	v_mfma_i32_16x16x64_i8 v[46:49], v[66:69], v[194:197], v[46:49]
	v_mfma_i32_16x16x64_i8 v[42:45], v[74:77], v[194:197], v[42:45]
	v_mfma_i32_16x16x64_i8 v[30:33], v[66:69], v[202:205], v[30:33]
	v_mfma_i32_16x16x64_i8 v[26:29], v[74:77], v[202:205], v[26:29]
	v_mfma_i32_16x16x64_i8 v[14:17], v[66:69], v[210:213], v[14:17]
	v_mfma_i32_16x16x64_i8 v[10:13], v[74:77], v[210:213], v[10:13]
	v_mfma_i32_16x16x64_i8 v[62:65], v[70:73], v[190:193], v[62:65]
	v_mfma_i32_16x16x64_i8 v[58:61], v[78:81], v[190:193], v[58:61]
	v_mfma_i32_16x16x64_i8 v[46:49], v[70:73], v[198:201], v[46:49]
	v_mfma_i32_16x16x64_i8 v[42:45], v[78:81], v[198:201], v[42:45]
	v_mfma_i32_16x16x64_i8 v[30:33], v[70:73], v[206:209], v[30:33]
	v_mfma_i32_16x16x64_i8 v[26:29], v[78:81], v[206:209], v[26:29]
	v_mfma_i32_16x16x64_i8 v[14:17], v[70:73], v[214:217], v[14:17]
	v_mfma_i32_16x16x64_i8 v[10:13], v[78:81], v[214:217], v[10:13]
	v_mfma_i32_16x16x64_i8 v[54:57], v[146:149], v[186:189], v[54:57]
	v_mfma_i32_16x16x64_i8 v[50:53], v[172:175], v[186:189], v[50:53]
	v_mfma_i32_16x16x64_i8 v[38:41], v[146:149], v[194:197], v[38:41]
	v_mfma_i32_16x16x64_i8 v[34:37], v[172:175], v[194:197], v[34:37]
	v_mfma_i32_16x16x64_i8 v[22:25], v[146:149], v[202:205], v[22:25]
	v_mfma_i32_16x16x64_i8 v[18:21], v[172:175], v[202:205], v[18:21]
	v_mfma_i32_16x16x64_i8 v[6:9], v[146:149], v[210:213], v[6:9]
	v_mfma_i32_16x16x64_i8 v[2:5], v[172:175], v[210:213], v[2:5]
	v_mfma_i32_16x16x64_i8 v[54:57], v[150:153], v[190:193], v[54:57]
	v_mfma_i32_16x16x64_i8 v[50:53], v[182:185], v[190:193], v[50:53]
	v_mfma_i32_16x16x64_i8 v[38:41], v[150:153], v[198:201], v[38:41]
	v_mfma_i32_16x16x64_i8 v[34:37], v[182:185], v[198:201], v[34:37]
	v_mfma_i32_16x16x64_i8 v[22:25], v[150:153], v[206:209], v[22:25]
	v_mfma_i32_16x16x64_i8 v[18:21], v[182:185], v[206:209], v[18:21]
	v_mfma_i32_16x16x64_i8 v[6:9], v[150:153], v[214:217], v[6:9]
	v_mfma_i32_16x16x64_i8 v[2:5], v[182:185], v[214:217], v[2:5]
	s_barrier
; #define PG8_STAGE(bufoff, gbase, voff) do { _Pragma("unroll") for (int _i = 0; _i < 2; ++_i) \
;         __builtin_amdgcn_global_load_lds((const unsigned*)((const char*)(gbase) + (voff)[_i]), (LAS unsigned*)(lds + (bufoff) + ldsw + _i * 8192), 16, 0, 0); } while (0)
; #define PG8_LDA(dst, b, h) do { _Pragma("unroll") for (int m = 0; m < 4; ++m) _Pragma("unroll") for (int k = 0; k < 2; ++k) dst[m][k] = *(const LAS bf16x8*)(lds + PG8_SA(b, h) + aoff + m * 2048 + k * 1024); } while (0)
; #define PG8_LDB(dst, b, h) do { _Pragma("unroll") for (int n = 0; n < 2; ++n) _Pragma("unroll") for (int k = 0; k < 2; ++k) dst[n][k] = *(const LAS bf16x8*)(lds + PG8_SB(b, h) + boff + n * 2048 + k * 1024); } while (0)
; #define PG8_WAIT_V(n) asm volatile("s_waitcnt vmcnt(" #n ")" ::: "memory")
; template <class Epi, class Sched, bool I8 = false>
; __device__ __forceinline__ void gemm_phase(LAS unsigned char* lds, const Gemm g, const Sched& S, const Epi& E) {
;     ...
;         for (int t = 0; t < nt; t += 2) {
;             const bool last = (t == nt - 2);
;             const char* a1 = cA + (size_t)(t + 1) * kstep;
;             const char* a2 = last ? nA : cA + (size_t)(t + 2) * kstep; const char* b2 = last ? nB : cB + (size_t)(t + 2) * kstep;
;             const char* a3 = a2 + kstep; const char* b3 = b2 + kstep;
;             PG8_LDB(B0, 0, 0); PG8_LDB(B1, 0, 1); PG8_SCHED; PG8_LDA(At, 0, 0); PG8_STAGE(PG8_SA(1, 1), a1 + hstepA, voffA);
;             PG8_WAIT_V(8); PG8_WAIT_L(0); PG8_BAR; PG8_MMA(0, 0, At, B0); PG8_MMA(0, 1, At, B1); PG8_BAR; PG8_SCHED;
;             PG8_LDA(At, 0, 1); PG8_STAGE(PG8_SB(0, 0), b2, voffB); PG8_STAGE(PG8_SB(0, 1), b2 + hstepB, voffB); PG8_STAGE(PG8_SA(0, 0), a2, voffA);
;             PG8_WAIT_V(8); PG8_WAIT_L(0); PG8_BAR; PG8_MMA(1, 0, At, B0); PG8_MMA(1, 1, At, B1); PG8_BAR; PG8_SCHED;
;             PG8_LDB(B0, 1, 0); PG8_LDB(B1, 1, 1); PG8_SCHED; PG8_LDA(At, 1, 0); PG8_STAGE(PG8_SA(0, 1), a2 + hstepA, voffA);
;             PG8_WAIT_V(8); PG8_WAIT_L(0); PG8_BAR; PG8_MMA(0, 0, At, B0); PG8_MMA(0, 1, At, B1); PG8_BAR; PG8_SCHED;
;             PG8_LDA(At, 1, 1); PG8_STAGE(PG8_SB(1, 0), b3, voffB); PG8_STAGE(PG8_SB(1, 1), b3 + hstepB, voffB); PG8_STAGE(PG8_SA(1, 0), a3, voffA);
;             PG8_WAIT_V(8); PG8_WAIT_L(0); PG8_BAR; PG8_MMA(1, 0, At, B0); PG8_MMA(1, 1, At, B1); PG8_BAR; PG8_SCHED;
;         }
;         if (wr == 0) PG8_BAR;
	s_setprio 1
	s_add_i32 s52, 0, 0x18000
	s_add_i32 s53, 0, 0x1c000
	v_add_u32_e32 v78, s52, v176
	v_add_u32_e32 v162, s53, v176
	ds_read_b128 v[66:69], v78
	ds_read_b128 v[70:73], v78 offset:1024
	ds_read_b128 v[74:77], v78 offset:2048
	ds_read_b128 v[78:81], v78 offset:3072
	ds_read_b128 v[146:149], v162
	ds_read_b128 v[150:153], v162 offset:1024
	ds_read_b128 v[172:175], v162 offset:2048
	ds_read_b128 v[182:185], v162 offset:3072
	s_mov_b32 m0, s34
	s_nop 0
	global_load_lds_dwordx4 v154, s[26:27]
	s_mov_b32 m0, s35
	s_nop 0
	global_load_lds_dwordx4 v158, s[26:27]
	s_add_u32 s26, s26, 0x4000
	s_addc_u32 s27, s27, 0
	s_mov_b32 m0, s36
	ds_read_b128 v[186:189], v180 offset:32768
	ds_read_b128 v[190:193], v180 offset:33792
	ds_read_b128 v[194:197], v180 offset:34816
	ds_read_b128 v[198:201], v180 offset:35840
	ds_read_b128 v[202:205], v180 offset:36864
	ds_read_b128 v[206:209], v180 offset:37888
	ds_read_b128 v[210:213], v180 offset:38912
	ds_read_b128 v[214:217], v180 offset:39936
	global_load_lds_dwordx4 v154, s[26:27]
	s_mov_b32 m0, s37
	s_nop 0
	global_load_lds_dwordx4 v158, s[26:27]
	s_setprio 0
	s_waitcnt vmcnt(8)
	s_waitcnt lgkmcnt(0)
	s_barrier
	s_waitcnt lgkmcnt(0)
	v_mfma_i32_16x16x64_i8 v[142:145], v[66:69], v[186:189], v[142:145]
	v_mfma_i32_16x16x64_i8 v[138:141], v[74:77], v[186:189], v[138:141]
	v_mfma_i32_16x16x64_i8 v[126:129], v[66:69], v[194:197], v[126:129]
	v_mfma_i32_16x16x64_i8 v[122:125], v[74:77], v[194:197], v[122:125]
	v_mfma_i32_16x16x64_i8 v[110:113], v[66:69], v[202:205], v[110:113]
	v_mfma_i32_16x16x64_i8 v[106:109], v[74:77], v[202:205], v[106:109]
	v_mfma_i32_16x16x64_i8 v[94:97], v[66:69], v[210:213], v[94:97]
	v_mfma_i32_16x16x64_i8 v[90:93], v[74:77], v[210:213], v[90:93]
	v_mfma_i32_16x16x64_i8 v[142:145], v[70:73], v[190:193], v[142:145]
	v_mfma_i32_16x16x64_i8 v[138:141], v[78:81], v[190:193], v[138:141]
	v_mfma_i32_16x16x64_i8 v[126:129], v[70:73], v[198:201], v[126:129]
	v_mfma_i32_16x16x64_i8 v[122:125], v[78:81], v[198:201], v[122:125]
	v_mfma_i32_16x16x64_i8 v[110:113], v[70:73], v[206:209], v[110:113]
	v_mfma_i32_16x16x64_i8 v[106:109], v[78:81], v[206:209], v[106:109]
	v_mfma_i32_16x16x64_i8 v[94:97], v[70:73], v[214:217], v[94:97]
	v_mfma_i32_16x16x64_i8 v[90:93], v[78:81], v[214:217], v[90:93]
	v_mfma_i32_16x16x64_i8 v[134:137], v[146:149], v[186:189], v[134:137]
	v_mfma_i32_16x16x64_i8 v[130:133], v[172:175], v[186:189], v[130:133]
	v_mfma_i32_16x16x64_i8 v[118:121], v[146:149], v[194:197], v[118:121]
	v_mfma_i32_16x16x64_i8 v[114:117], v[172:175], v[194:197], v[114:117]
	v_mfma_i32_16x16x64_i8 v[102:105], v[146:149], v[202:205], v[102:105]
	v_mfma_i32_16x16x64_i8 v[98:101], v[172:175], v[202:205], v[98:101]
	v_mfma_i32_16x16x64_i8 v[86:89], v[146:149], v[210:213], v[86:89]
	v_mfma_i32_16x16x64_i8 v[82:85], v[172:175], v[210:213], v[82:85]
	v_mfma_i32_16x16x64_i8 v[134:137], v[150:153], v[190:193], v[134:137]
	v_mfma_i32_16x16x64_i8 v[130:133], v[182:185], v[190:193], v[130:133]
	v_mfma_i32_16x16x64_i8 v[118:121], v[150:153], v[198:201], v[118:121]
	v_mfma_i32_16x16x64_i8 v[114:117], v[182:185], v[198:201], v[114:117]
	v_mfma_i32_16x16x64_i8 v[102:105], v[150:153], v[206:209], v[102:105]
	v_mfma_i32_16x16x64_i8 v[98:101], v[182:185], v[206:209], v[98:101]
	v_mfma_i32_16x16x64_i8 v[86:89], v[150:153], v[214:217], v[86:89]
	v_mfma_i32_16x16x64_i8 v[82:85], v[182:185], v[214:217], v[82:85]
	s_barrier
	s_setprio 1
	s_add_u32 s26, s24, 0x8000
	s_addc_u32 s27, s25, 0
	s_add_i32 s52, s52, s33
	s_mov_b32 m0, s52
	ds_read_b128 v[186:189], v180 offset:49152
	ds_read_b128 v[190:193], v180 offset:50176
	ds_read_b128 v[194:197], v180 offset:51200
	ds_read_b128 v[198:201], v180 offset:52224
	ds_read_b128 v[202:205], v180 offset:53248
	ds_read_b128 v[206:209], v180 offset:54272
	ds_read_b128 v[210:213], v180 offset:55296
	ds_read_b128 v[214:217], v180 offset:56320
	global_load_lds_dwordx4 v156, s[26:27]
	s_add_i32 m0, s52, 0x2000
	s_add_u32 s24, s24, 0xc000
	v_lshl_add_u64 v[218:219], s[26:27], 0, v[160:161]
	s_addc_u32 s25, s25, 0
	s_add_i32 s26, s53, s33
	global_load_lds_dwordx4 v[218:219], off
	s_mov_b32 m0, s26
	s_nop 0
	global_load_lds_dwordx4 v156, s[24:25]
	s_add_i32 m0, s26, 0x2000
	s_nop 0
	global_load_lds_dwordx4 v160, s[24:25]
	s_setprio 0
	s_waitcnt vmcnt(6)
	s_waitcnt lgkmcnt(0)
	s_barrier
	s_waitcnt lgkmcnt(0)
	v_mfma_i32_16x16x64_i8 v[62:65], v[66:69], v[186:189], v[62:65]
	v_mfma_i32_16x16x64_i8 v[58:61], v[74:77], v[186:189], v[58:61]
	v_mfma_i32_16x16x64_i8 v[46:49], v[66:69], v[194:197], v[46:49]
	v_mfma_i32_16x16x64_i8 v[42:45], v[74:77], v[194:197], v[42:45]
	v_mfma_i32_16x16x64_i8 v[30:33], v[66:69], v[202:205], v[30:33]
	v_mfma_i32_16x16x64_i8 v[26:29], v[74:77], v[202:205], v[26:29]
	v_mfma_i32_16x16x64_i8 v[14:17], v[66:69], v[210:213], v[14:17]
	v_mfma_i32_16x16x64_i8 v[10:13], v[74:77], v[210:213], v[10:13]
	v_mfma_i32_16x16x64_i8 v[62:65], v[70:73], v[190:193], v[62:65]
	v_mfma_i32_16x16x64_i8 v[58:61], v[78:81], v[190:193], v[58:61]
	v_mfma_i32_16x16x64_i8 v[46:49], v[70:73], v[198:201], v[46:49]
	v_mfma_i32_16x16x64_i8 v[42:45], v[78:81], v[198:201], v[42:45]
	v_mfma_i32_16x16x64_i8 v[30:33], v[70:73], v[206:209], v[30:33]
	v_mfma_i32_16x16x64_i8 v[26:29], v[78:81], v[206:209], v[26:29]
	v_mfma_i32_16x16x64_i8 v[14:17], v[70:73], v[214:217], v[14:17]
	v_mfma_i32_16x16x64_i8 v[10:13], v[78:81], v[214:217], v[10:13]
	v_mfma_i32_16x16x64_i8 v[54:57], v[146:149], v[186:189], v[54:57]
	v_mfma_i32_16x16x64_i8 v[50:53], v[172:175], v[186:189], v[50:53]
	v_mfma_i32_16x16x64_i8 v[38:41], v[146:149], v[194:197], v[38:41]
	v_mfma_i32_16x16x64_i8 v[34:37], v[172:175], v[194:197], v[34:37]
	v_mfma_i32_16x16x64_i8 v[22:25], v[146:149], v[202:205], v[22:25]
	v_mfma_i32_16x16x64_i8 v[18:21], v[172:175], v[202:205], v[18:21]
	v_mfma_i32_16x16x64_i8 v[6:9], v[146:149], v[210:213], v[6:9]
	v_mfma_i32_16x16x64_i8 v[2:5], v[172:175], v[210:213], v[2:5]
	v_mfma_i32_16x16x64_i8 v[54:57], v[150:153], v[190:193], v[54:57]
	v_mfma_i32_16x16x64_i8 v[50:53], v[182:185], v[190:193], v[50:53]
	v_mfma_i32_16x16x64_i8 v[38:41], v[150:153], v[198:201], v[38:41]
	v_mfma_i32_16x16x64_i8 v[34:37], v[182:185], v[198:201], v[34:37]
	v_mfma_i32_16x16x64_i8 v[22:25], v[150:153], v[206:209], v[22:25]
	v_mfma_i32_16x16x64_i8 v[18:21], v[182:185], v[206:209], v[18:21]
	v_mfma_i32_16x16x64_i8 v[6:9], v[150:153], v[214:217], v[6:9]
	v_mfma_i32_16x16x64_i8 v[2:5], v[182:185], v[214:217], v[2:5]
	s_barrier
	s_add_i32 s51, s51, 2
	s_add_u32 s20, s20, 0x10000
	s_addc_u32 s21, s21, 0
	s_add_u32 s49, s49, 0x10000
	s_addc_u32 s50, s50, 0
	s_cmpk_gt_u32 s51, 0x53
	s_cbranch_scc0 .LBB0_4168
	s_and_b64 vcc, exec, s[14:15]
	s_cbranch_vccz .LBB0_4171
	s_barrier
